# DPP row ops + permlane16/32 swaps instead of ds_bpermute for the row-norm sums, prep0/prep2 head-norm sums and rope exchanges; gla_out loads issued together
# speedup vs baseline: 1.0124x; 1.0063x over previous
.LBB0_257:
	v_add_u32_e32 v1, s2, v28
	v_mov_b32_e32 v4, 0x2000
	v_cndmask_b32_e64 v1, v4, v1, s[0:1]
	v_cmp_lt_i32_e32 vcc, v28, v1
	s_and_saveexec_b64 s[0:1], vcc
	v_readlane_b32 s5, v254, 7
	s_movk_i32 s2, 0xfff
	s_mov_b64 s[14:15], 0x1000
	s_mul_i32 s16, s5, 3
	s_cbranch_execz .LBB0_260
	v_readlane_b32 s5, v254, 7
	s_lshl_b32 s8, s5, 10
	s_ashr_i32 s9, s8, 31
	s_lshl_b64 s[8:9], s[8:9], 2
	v_lshlrev_b32_e32 v4, 2, v2
	s_add_u32 s8, s6, s8
	v_and_b32_e32 v4, 0xfc, v4
	s_addc_u32 s9, s7, s9
	v_and_b32_e32 v5, 64, v223
	v_lshlrev_b32_e32 v6, 2, v4
	v_mov_b32_e32 v7, v3
	v_add_u32_e32 v5, 64, v5
	v_lshl_add_u64 v[30:31], s[8:9], 0, v[6:7]
	v_xor_b32_e32 v6, 32, v223
	v_cmp_lt_i32_e32 vcc, v6, v5
	s_load_dwordx2 s[10:11], s[30:31], 0x170
	v_ashrrev_i32_e32 v29, 31, v28
	v_cndmask_b32_e32 v6, v223, v6, vcc
	v_lshlrev_b32_e32 v37, 2, v6
	v_xor_b32_e32 v6, 16, v223
	v_cmp_lt_i32_e32 vcc, v6, v5
	v_lshlrev_b64 v[12:13], 11, v[28:29]
	v_and_b32_e32 v2, 63, v2
	v_cndmask_b32_e32 v6, v223, v6, vcc
	v_lshlrev_b32_e32 v56, 2, v6
	v_xor_b32_e32 v6, 8, v223
	v_cmp_lt_i32_e32 vcc, v6, v5
	v_readlane_b32 s8, v254, 16
	v_lshl_or_b32 v12, v2, 3, v12
	v_cndmask_b32_e32 v6, v223, v6, vcc
	v_lshlrev_b32_e32 v57, 2, v6
	v_xor_b32_e32 v6, 4, v223
	v_cmp_lt_i32_e32 vcc, v6, v5
	v_readlane_b32 s9, v254, 17
	s_add_u32 s6, s28, 0xd823000
	v_cndmask_b32_e32 v6, v223, v6, vcc
	v_lshlrev_b32_e32 v58, 2, v6
	v_xor_b32_e32 v6, 2, v223
	v_cmp_lt_i32_e32 vcc, v6, v5
	v_lshl_add_u64 v[32:33], s[8:9], 0, v[12:13]
	v_lshlrev_b64 v[12:13], 12, v[28:29]
	v_cndmask_b32_e32 v6, v223, v6, vcc
	v_lshlrev_b32_e32 v59, 2, v6
	v_xor_b32_e32 v6, 1, v223
	v_cmp_lt_i32_e32 vcc, v6, v5
	s_addc_u32 s7, s29, 0
	v_or_b32_e32 v8, 0x200, v4
	v_cndmask_b32_e32 v5, v223, v6, vcc
	v_or_b32_e32 v6, 0x100, v4
	v_or_b32_e32 v10, 0x300, v4
	s_ashr_i32 s5, s4, 31
	v_lshl_or_b32 v12, v2, 4, v12
	v_lshlrev_b32_e32 v60, 2, v5
	s_lshl_b64 s[8:9], s[4:5], 11
	s_waitcnt lgkmcnt(0)
	v_lshl_add_u64 v[34:35], s[10:11], 0, v[12:13]
	s_lshl_b64 s[10:11], s[4:5], 12
	s_mov_b64 s[12:13], 0
	v_lshlrev_b32_e32 v2, 2, v4
	v_lshlrev_b32_e32 v38, 2, v6
	v_lshlrev_b32_e32 v40, 2, v8
	v_lshlrev_b32_e32 v42, 2, v10
	v_sub_u32_e32 v4, v1, v28
	s_nop 0
	v_readfirstlane_b32 s5, v4
	s_cmp_eq_u32 s5, 4
	s_cbranch_scc0 .LBB0_259
	s_cmp_eq_u32 s4, 1
	s_cbranch_scc0 .LBB0_259
	v_cmp_gt_i32_e32 vcc, s67, v28
	s_nop 1
	v_cndmask_b32_e64 v4, 2, 1, vcc
	v_cmp_lt_i32_e32 vcc, s2, v28
	s_nop 1
	v_cndmask_b32_e32 v4, 0, v4, vcc
	v_add_u32_e32 v4, s16, v4
	v_mul_i32_i24_e32 v4, 0x6000, v4
	v_ashrrev_i32_e32 v5, 31, v4
	v_lshl_add_u64 v[146:147], s[6:7], 0, v[4:5]
	v_lshl_add_u64 v[148:149], v[146:147], 0, v[2:3]
	v_lshl_add_u64 v[150:151], v[148:149], 0, s[14:15]
	global_load_dwordx4 v[80:83], v[30:31], off
	global_load_dwordx4 v[84:87], v[30:31], off offset:1024
	global_load_dwordx4 v[88:91], v[30:31], off offset:2048
	global_load_dwordx4 v[92:95], v[30:31], off offset:3072
	global_load_dwordx4 v[96:99], v[148:149], off
	global_load_dwordx4 v[100:103], v[148:149], off offset:1024
	global_load_dwordx4 v[104:107], v[148:149], off offset:2048
	global_load_dwordx4 v[108:111], v[148:149], off offset:3072
	global_load_dwordx4 v[112:115], v[150:151], off
	global_load_dwordx4 v[116:119], v[150:151], off offset:1024
	global_load_dwordx4 v[120:123], v[150:151], off offset:2048
	global_load_dwordx4 v[124:127], v[150:151], off offset:3072
	global_load_dwordx4 v[188:191], v[34:35], off
	global_load_dwordx4 v[192:195], v[34:35], off offset:1024
	global_load_dwordx4 v[196:199], v[34:35], off offset:2048
	global_load_dwordx4 v[200:203], v[34:35], off offset:3072
	v_lshl_add_u64 v[152:153], v[34:35], 0, s[10:11]
	global_load_dwordx4 v[204:207], v[152:153], off
	global_load_dwordx4 v[208:211], v[152:153], off offset:1024
	global_load_dwordx4 v[212:215], v[152:153], off offset:2048
	global_load_dwordx4 v[234:237], v[152:153], off offset:3072
	v_lshl_add_u64 v[152:153], v[152:153], 0, s[10:11]
	global_load_dwordx4 v[238:241], v[152:153], off
	global_load_dwordx4 v[242:245], v[152:153], off offset:1024
	global_load_dwordx4 v[246:249], v[152:153], off offset:2048
	global_load_dwordx4 v[250:253], v[152:153], off offset:3072
	v_lshl_add_u64 v[152:153], v[152:153], 0, s[10:11]
	global_load_dwordx4 v[128:131], v[152:153], off
	global_load_dwordx4 v[132:135], v[152:153], off offset:1024
	global_load_dwordx4 v[136:139], v[152:153], off offset:2048
	global_load_dwordx4 v[142:145], v[152:153], off offset:3072
	s_waitcnt vmcnt(12)
	v_mul_f32_e32 v170, v189, v189
	v_fma_f32 v170, v188, v188, v170
	v_fma_f32 v170, v190, v190, v170
	v_fma_f32 v170, v191, v191, v170
	v_mul_f32_e32 v171, v193, v193
	v_fma_f32 v171, v192, v192, v171
	v_fma_f32 v171, v194, v194, v171
	v_fma_f32 v171, v195, v195, v171
	v_add_f32_e32 v158, v170, v171
	v_mul_f32_e32 v170, v197, v197
	v_fma_f32 v170, v196, v196, v170
	v_fma_f32 v170, v198, v198, v170
	v_fma_f32 v170, v199, v199, v170
	v_mul_f32_e32 v171, v201, v201
	v_fma_f32 v171, v200, v200, v171
	v_fma_f32 v171, v202, v202, v171
	v_fma_f32 v171, v203, v203, v171
	v_add_f32_e32 v158, v158, v170
	v_add_f32_e32 v158, v158, v171
	s_waitcnt vmcnt(8)
	v_mul_f32_e32 v170, v205, v205
	v_fma_f32 v170, v204, v204, v170
	v_fma_f32 v170, v206, v206, v170
	v_fma_f32 v170, v207, v207, v170
	v_mul_f32_e32 v171, v209, v209
	v_fma_f32 v171, v208, v208, v171
	v_fma_f32 v171, v210, v210, v171
	v_fma_f32 v171, v211, v211, v171
	v_add_f32_e32 v160, v170, v171
	v_mul_f32_e32 v170, v213, v213
	v_fma_f32 v170, v212, v212, v170
	v_fma_f32 v170, v214, v214, v170
	v_fma_f32 v170, v215, v215, v170
	v_mul_f32_e32 v171, v235, v235
	v_fma_f32 v171, v234, v234, v171
	v_fma_f32 v171, v236, v236, v171
	v_fma_f32 v171, v237, v237, v171
	v_add_f32_e32 v160, v160, v170
	v_add_f32_e32 v160, v160, v171
	s_waitcnt vmcnt(4)
	v_mul_f32_e32 v170, v239, v239
	v_fma_f32 v170, v238, v238, v170
	v_fma_f32 v170, v240, v240, v170
	v_fma_f32 v170, v241, v241, v170
	v_mul_f32_e32 v171, v243, v243
	v_fma_f32 v171, v242, v242, v171
	v_fma_f32 v171, v244, v244, v171
	v_fma_f32 v171, v245, v245, v171
	v_add_f32_e32 v162, v170, v171
	v_mul_f32_e32 v170, v247, v247
	v_fma_f32 v170, v246, v246, v170
	v_fma_f32 v170, v248, v248, v170
	v_fma_f32 v170, v249, v249, v170
	v_mul_f32_e32 v171, v251, v251
	v_fma_f32 v171, v250, v250, v171
	v_fma_f32 v171, v252, v252, v171
	v_fma_f32 v171, v253, v253, v171
	v_add_f32_e32 v162, v162, v170
	v_add_f32_e32 v162, v162, v171
	s_waitcnt vmcnt(0)
	v_mul_f32_e32 v170, v129, v129
	v_fma_f32 v170, v128, v128, v170
	v_fma_f32 v170, v130, v130, v170
	v_fma_f32 v170, v131, v131, v170
	v_mul_f32_e32 v171, v133, v133
	v_fma_f32 v171, v132, v132, v171
	v_fma_f32 v171, v134, v134, v171
	v_fma_f32 v171, v135, v135, v171
	v_add_f32_e32 v164, v170, v171
	v_mul_f32_e32 v170, v137, v137
	v_fma_f32 v170, v136, v136, v170
	v_fma_f32 v170, v138, v138, v170
	v_fma_f32 v170, v139, v139, v170
	v_mul_f32_e32 v171, v143, v143
	v_fma_f32 v171, v142, v142, v171
	v_fma_f32 v171, v144, v144, v171
	v_fma_f32 v171, v145, v145, v171
	v_add_f32_e32 v164, v164, v170
	v_add_f32_e32 v164, v164, v171
	s_nop 1
	v_add_f32_dpp v158, v158, v158 quad_perm:[1,0,3,2] row_mask:0xf bank_mask:0xf
	v_add_f32_dpp v160, v160, v160 quad_perm:[1,0,3,2] row_mask:0xf bank_mask:0xf
	v_add_f32_dpp v162, v162, v162 quad_perm:[1,0,3,2] row_mask:0xf bank_mask:0xf
	v_add_f32_dpp v164, v164, v164 quad_perm:[1,0,3,2] row_mask:0xf bank_mask:0xf
	v_add_f32_dpp v158, v158, v158 quad_perm:[2,3,0,1] row_mask:0xf bank_mask:0xf
	v_add_f32_dpp v160, v160, v160 quad_perm:[2,3,0,1] row_mask:0xf bank_mask:0xf
	v_add_f32_dpp v162, v162, v162 quad_perm:[2,3,0,1] row_mask:0xf bank_mask:0xf
	v_add_f32_dpp v164, v164, v164 quad_perm:[2,3,0,1] row_mask:0xf bank_mask:0xf
	v_add_f32_dpp v158, v158, v158 row_half_mirror row_mask:0xf bank_mask:0xf
	v_add_f32_dpp v160, v160, v160 row_half_mirror row_mask:0xf bank_mask:0xf
	v_add_f32_dpp v162, v162, v162 row_half_mirror row_mask:0xf bank_mask:0xf
	v_add_f32_dpp v164, v164, v164 row_half_mirror row_mask:0xf bank_mask:0xf
	v_add_f32_dpp v158, v158, v158 row_mirror row_mask:0xf bank_mask:0xf
	v_add_f32_dpp v160, v160, v160 row_mirror row_mask:0xf bank_mask:0xf
	v_add_f32_dpp v162, v162, v162 row_mirror row_mask:0xf bank_mask:0xf
	v_add_f32_dpp v164, v164, v164 row_mirror row_mask:0xf bank_mask:0xf
	v_mov_b32_e32 v166, v158
	v_mov_b32_e32 v167, v160
	v_mov_b32_e32 v168, v162
	v_mov_b32_e32 v169, v164
	v_permlane16_swap_b32 v158, v166
	v_permlane16_swap_b32 v160, v167
	v_permlane16_swap_b32 v162, v168
	v_permlane16_swap_b32 v164, v169
	v_add_f32_e32 v158, v158, v166
	v_add_f32_e32 v160, v160, v167
	v_add_f32_e32 v162, v162, v168
	v_add_f32_e32 v164, v164, v169
	v_mov_b32_e32 v166, v158
	v_mov_b32_e32 v167, v160
	v_mov_b32_e32 v168, v162
	v_mov_b32_e32 v169, v164
	v_permlane32_swap_b32 v158, v166
	v_permlane32_swap_b32 v160, v167
	v_permlane32_swap_b32 v162, v168
	v_permlane32_swap_b32 v164, v169
	v_add_f32_e32 v158, v158, v166
	v_add_f32_e32 v160, v160, v167
	v_add_f32_e32 v162, v162, v168
	v_add_f32_e32 v164, v164, v169
	v_pk_add_f32 v[112:113], v[112:113], 1.0 op_sel_hi:[1,0]
	v_pk_add_f32 v[114:115], v[114:115], 1.0 op_sel_hi:[1,0]
	v_pk_add_f32 v[116:117], v[116:117], 1.0 op_sel_hi:[1,0]
	v_pk_add_f32 v[118:119], v[118:119], 1.0 op_sel_hi:[1,0]
	v_pk_add_f32 v[120:121], v[120:121], 1.0 op_sel_hi:[1,0]
	v_pk_add_f32 v[122:123], v[122:123], 1.0 op_sel_hi:[1,0]
	v_pk_add_f32 v[124:125], v[124:125], 1.0 op_sel_hi:[1,0]
	v_pk_add_f32 v[126:127], v[126:127], 1.0 op_sel_hi:[1,0]
	v_fmamk_f32 v158, v158, 0x3a800000, v218
	v_cmp_gt_f32_e32 vcc, s71, v158
	v_mul_f32_e32 v170, 0x4b800000, v158
	s_nop 0
	v_cndmask_b32_e32 v158, v158, v170, vcc
	v_rsq_f32_e32 v158, v158
	s_nop 0
	v_mul_f32_e32 v170, 0x45800000, v158
	v_cndmask_b32_e32 v158, v158, v170, vcc
	v_fmamk_f32 v160, v160, 0x3a800000, v218
	v_cmp_gt_f32_e32 vcc, s71, v160
	v_mul_f32_e32 v170, 0x4b800000, v160
	s_nop 0
	v_cndmask_b32_e32 v160, v160, v170, vcc
	v_rsq_f32_e32 v160, v160
	s_nop 0
	v_mul_f32_e32 v170, 0x45800000, v160
	v_cndmask_b32_e32 v160, v160, v170, vcc
	v_fmamk_f32 v162, v162, 0x3a800000, v218
	v_cmp_gt_f32_e32 vcc, s71, v162
	v_mul_f32_e32 v170, 0x4b800000, v162
	s_nop 0
	v_cndmask_b32_e32 v162, v162, v170, vcc
	v_rsq_f32_e32 v162, v162
	s_nop 0
	v_mul_f32_e32 v170, 0x45800000, v162
	v_cndmask_b32_e32 v162, v162, v170, vcc
	v_fmamk_f32 v164, v164, 0x3a800000, v218
	v_cmp_gt_f32_e32 vcc, s71, v164
	v_mul_f32_e32 v170, 0x4b800000, v164
	s_nop 0
	v_cndmask_b32_e32 v164, v164, v170, vcc
	v_rsq_f32_e32 v164, v164
	s_nop 0
	v_mul_f32_e32 v170, 0x45800000, v164
	v_cndmask_b32_e32 v164, v164, v170, vcc
	v_pk_mul_f32 v[188:189], v[188:189], v[158:159] op_sel_hi:[1,0]
	v_pk_mul_f32 v[188:189], v[188:189], v[80:81]
	v_pk_fma_f32 v[188:189], v[188:189], v[112:113], v[96:97]
	v_pk_mul_f32 v[190:191], v[190:191], v[158:159] op_sel_hi:[1,0]
	v_pk_mul_f32 v[190:191], v[190:191], v[82:83]
	v_pk_fma_f32 v[190:191], v[190:191], v[114:115], v[98:99]
	v_cvt_pk_bf16_f32 v188, v188, v189
	v_cvt_pk_bf16_f32 v189, v190, v191
	global_store_dwordx2 v[32:33], v[188:189], off
	v_pk_mul_f32 v[192:193], v[192:193], v[158:159] op_sel_hi:[1,0]
	v_pk_mul_f32 v[192:193], v[192:193], v[84:85]
	v_pk_fma_f32 v[192:193], v[192:193], v[116:117], v[100:101]
	v_pk_mul_f32 v[194:195], v[194:195], v[158:159] op_sel_hi:[1,0]
	v_pk_mul_f32 v[194:195], v[194:195], v[86:87]
	v_pk_fma_f32 v[194:195], v[194:195], v[118:119], v[102:103]
	v_cvt_pk_bf16_f32 v192, v192, v193
	v_cvt_pk_bf16_f32 v193, v194, v195
	global_store_dwordx2 v[32:33], v[192:193], off offset:512
	v_pk_mul_f32 v[196:197], v[196:197], v[158:159] op_sel_hi:[1,0]
	v_pk_mul_f32 v[196:197], v[196:197], v[88:89]
	v_pk_fma_f32 v[196:197], v[196:197], v[120:121], v[104:105]
	v_pk_mul_f32 v[198:199], v[198:199], v[158:159] op_sel_hi:[1,0]
	v_pk_mul_f32 v[198:199], v[198:199], v[90:91]
	v_pk_fma_f32 v[198:199], v[198:199], v[122:123], v[106:107]
	v_cvt_pk_bf16_f32 v196, v196, v197
	v_cvt_pk_bf16_f32 v197, v198, v199
	global_store_dwordx2 v[32:33], v[196:197], off offset:1024
	v_pk_mul_f32 v[200:201], v[200:201], v[158:159] op_sel_hi:[1,0]
	v_pk_mul_f32 v[200:201], v[200:201], v[92:93]
	v_pk_fma_f32 v[200:201], v[200:201], v[124:125], v[108:109]
	v_pk_mul_f32 v[202:203], v[202:203], v[158:159] op_sel_hi:[1,0]
	v_pk_mul_f32 v[202:203], v[202:203], v[94:95]
	v_pk_fma_f32 v[202:203], v[202:203], v[126:127], v[110:111]
	v_cvt_pk_bf16_f32 v200, v200, v201
	v_cvt_pk_bf16_f32 v201, v202, v203
	global_store_dwordx2 v[32:33], v[200:201], off offset:1536
	v_lshl_add_u64 v[154:155], v[32:33], 0, s[8:9]
	v_pk_mul_f32 v[204:205], v[204:205], v[160:161] op_sel_hi:[1,0]
	v_pk_mul_f32 v[204:205], v[204:205], v[80:81]
	v_pk_fma_f32 v[204:205], v[204:205], v[112:113], v[96:97]
	v_pk_mul_f32 v[206:207], v[206:207], v[160:161] op_sel_hi:[1,0]
	v_pk_mul_f32 v[206:207], v[206:207], v[82:83]
	v_pk_fma_f32 v[206:207], v[206:207], v[114:115], v[98:99]
	v_cvt_pk_bf16_f32 v204, v204, v205
	v_cvt_pk_bf16_f32 v205, v206, v207
	global_store_dwordx2 v[154:155], v[204:205], off
	v_pk_mul_f32 v[208:209], v[208:209], v[160:161] op_sel_hi:[1,0]
	v_pk_mul_f32 v[208:209], v[208:209], v[84:85]
	v_pk_fma_f32 v[208:209], v[208:209], v[116:117], v[100:101]
	v_pk_mul_f32 v[210:211], v[210:211], v[160:161] op_sel_hi:[1,0]
	v_pk_mul_f32 v[210:211], v[210:211], v[86:87]
	v_pk_fma_f32 v[210:211], v[210:211], v[118:119], v[102:103]
	v_cvt_pk_bf16_f32 v208, v208, v209
	v_cvt_pk_bf16_f32 v209, v210, v211
	global_store_dwordx2 v[154:155], v[208:209], off offset:512
	v_pk_mul_f32 v[212:213], v[212:213], v[160:161] op_sel_hi:[1,0]
	v_pk_mul_f32 v[212:213], v[212:213], v[88:89]
	v_pk_fma_f32 v[212:213], v[212:213], v[120:121], v[104:105]
	v_pk_mul_f32 v[214:215], v[214:215], v[160:161] op_sel_hi:[1,0]
	v_pk_mul_f32 v[214:215], v[214:215], v[90:91]
	v_pk_fma_f32 v[214:215], v[214:215], v[122:123], v[106:107]
	v_cvt_pk_bf16_f32 v212, v212, v213
	v_cvt_pk_bf16_f32 v213, v214, v215
	global_store_dwordx2 v[154:155], v[212:213], off offset:1024
	v_pk_mul_f32 v[234:235], v[234:235], v[160:161] op_sel_hi:[1,0]
	v_pk_mul_f32 v[234:235], v[234:235], v[92:93]
	v_pk_fma_f32 v[234:235], v[234:235], v[124:125], v[108:109]
	v_pk_mul_f32 v[236:237], v[236:237], v[160:161] op_sel_hi:[1,0]
	v_pk_mul_f32 v[236:237], v[236:237], v[94:95]
	v_pk_fma_f32 v[236:237], v[236:237], v[126:127], v[110:111]
	v_cvt_pk_bf16_f32 v234, v234, v235
	v_cvt_pk_bf16_f32 v235, v236, v237
	global_store_dwordx2 v[154:155], v[234:235], off offset:1536
	v_lshl_add_u64 v[154:155], v[154:155], 0, s[8:9]
	v_pk_mul_f32 v[238:239], v[238:239], v[162:163] op_sel_hi:[1,0]
	v_pk_mul_f32 v[238:239], v[238:239], v[80:81]
	v_pk_fma_f32 v[238:239], v[238:239], v[112:113], v[96:97]
	v_pk_mul_f32 v[240:241], v[240:241], v[162:163] op_sel_hi:[1,0]
	v_pk_mul_f32 v[240:241], v[240:241], v[82:83]
	v_pk_fma_f32 v[240:241], v[240:241], v[114:115], v[98:99]
	v_cvt_pk_bf16_f32 v238, v238, v239
	v_cvt_pk_bf16_f32 v239, v240, v241
	global_store_dwordx2 v[154:155], v[238:239], off
	v_pk_mul_f32 v[242:243], v[242:243], v[162:163] op_sel_hi:[1,0]
	v_pk_mul_f32 v[242:243], v[242:243], v[84:85]
	v_pk_fma_f32 v[242:243], v[242:243], v[116:117], v[100:101]
	v_pk_mul_f32 v[244:245], v[244:245], v[162:163] op_sel_hi:[1,0]
	v_pk_mul_f32 v[244:245], v[244:245], v[86:87]
	v_pk_fma_f32 v[244:245], v[244:245], v[118:119], v[102:103]
	v_cvt_pk_bf16_f32 v242, v242, v243
	v_cvt_pk_bf16_f32 v243, v244, v245
	global_store_dwordx2 v[154:155], v[242:243], off offset:512
	v_pk_mul_f32 v[246:247], v[246:247], v[162:163] op_sel_hi:[1,0]
	v_pk_mul_f32 v[246:247], v[246:247], v[88:89]
	v_pk_fma_f32 v[246:247], v[246:247], v[120:121], v[104:105]
	v_pk_mul_f32 v[248:249], v[248:249], v[162:163] op_sel_hi:[1,0]
	v_pk_mul_f32 v[248:249], v[248:249], v[90:91]
	v_pk_fma_f32 v[248:249], v[248:249], v[122:123], v[106:107]
	v_cvt_pk_bf16_f32 v246, v246, v247
	v_cvt_pk_bf16_f32 v247, v248, v249
	global_store_dwordx2 v[154:155], v[246:247], off offset:1024
	v_pk_mul_f32 v[250:251], v[250:251], v[162:163] op_sel_hi:[1,0]
	v_pk_mul_f32 v[250:251], v[250:251], v[92:93]
	v_pk_fma_f32 v[250:251], v[250:251], v[124:125], v[108:109]
	v_pk_mul_f32 v[252:253], v[252:253], v[162:163] op_sel_hi:[1,0]
	v_pk_mul_f32 v[252:253], v[252:253], v[94:95]
	v_pk_fma_f32 v[252:253], v[252:253], v[126:127], v[110:111]
	v_cvt_pk_bf16_f32 v250, v250, v251
	v_cvt_pk_bf16_f32 v251, v252, v253
	global_store_dwordx2 v[154:155], v[250:251], off offset:1536
	v_lshl_add_u64 v[154:155], v[154:155], 0, s[8:9]
	v_pk_mul_f32 v[128:129], v[128:129], v[164:165] op_sel_hi:[1,0]
	v_pk_mul_f32 v[128:129], v[128:129], v[80:81]
	v_pk_fma_f32 v[128:129], v[128:129], v[112:113], v[96:97]
	v_pk_mul_f32 v[130:131], v[130:131], v[164:165] op_sel_hi:[1,0]
	v_pk_mul_f32 v[130:131], v[130:131], v[82:83]
	v_pk_fma_f32 v[130:131], v[130:131], v[114:115], v[98:99]
	v_cvt_pk_bf16_f32 v128, v128, v129
	v_cvt_pk_bf16_f32 v129, v130, v131
	global_store_dwordx2 v[154:155], v[128:129], off
	v_pk_mul_f32 v[132:133], v[132:133], v[164:165] op_sel_hi:[1,0]
	v_pk_mul_f32 v[132:133], v[132:133], v[84:85]
	v_pk_fma_f32 v[132:133], v[132:133], v[116:117], v[100:101]
	v_pk_mul_f32 v[134:135], v[134:135], v[164:165] op_sel_hi:[1,0]
	v_pk_mul_f32 v[134:135], v[134:135], v[86:87]
	v_pk_fma_f32 v[134:135], v[134:135], v[118:119], v[102:103]
	v_cvt_pk_bf16_f32 v132, v132, v133
	v_cvt_pk_bf16_f32 v133, v134, v135
	global_store_dwordx2 v[154:155], v[132:133], off offset:512
	v_pk_mul_f32 v[136:137], v[136:137], v[164:165] op_sel_hi:[1,0]
	v_pk_mul_f32 v[136:137], v[136:137], v[88:89]
	v_pk_fma_f32 v[136:137], v[136:137], v[120:121], v[104:105]
	v_pk_mul_f32 v[138:139], v[138:139], v[164:165] op_sel_hi:[1,0]
	v_pk_mul_f32 v[138:139], v[138:139], v[90:91]
	v_pk_fma_f32 v[138:139], v[138:139], v[122:123], v[106:107]
	v_cvt_pk_bf16_f32 v136, v136, v137
	v_cvt_pk_bf16_f32 v137, v138, v139
	global_store_dwordx2 v[154:155], v[136:137], off offset:1024
	v_pk_mul_f32 v[142:143], v[142:143], v[164:165] op_sel_hi:[1,0]
	v_pk_mul_f32 v[142:143], v[142:143], v[92:93]
	v_pk_fma_f32 v[142:143], v[142:143], v[124:125], v[108:109]
	v_pk_mul_f32 v[144:145], v[144:145], v[164:165] op_sel_hi:[1,0]
	v_pk_mul_f32 v[144:145], v[144:145], v[94:95]
	v_pk_fma_f32 v[144:145], v[144:145], v[126:127], v[110:111]
	v_cvt_pk_bf16_f32 v142, v142, v143
	v_cvt_pk_bf16_f32 v143, v144, v145
	global_store_dwordx2 v[154:155], v[142:143], off offset:1536
	s_branch .LBB0_260

.LBB0_501:
	v_ashrrev_i32_e32 v18, 7, v1
	v_ashrrev_i32_e32 v19, 31, v18
	v_and_b32_e32 v2, 0x3f8, v13
	v_lshlrev_b64 v[4:5], 11, v[18:19]
	v_lshl_add_u64 v[6:7], s[12:13], 0, v[4:5]
	v_lshlrev_b32_e32 v2, 1, v2
	v_lshl_add_u64 v[20:21], v[6:7], 0, v[2:3]
	global_load_dwordx4 v[14:17], v[20:21], off
	s_mov_b32 s14, 0x1000000
	v_add_co_u32_e32 v80, vcc, s14, v20
	s_nop 1
	v_addc_co_u32_e32 v81, vcc, 0, v21, vcc
	global_load_dwordx4 v[56:59], v[80:81], off
	v_mov_b64_e32 v[80:81], s[28:29]
	v_mad_i64_i32 v[80:81], s[14:15], v18, s16, v[80:81]
	v_lshl_add_u64 v[80:81], v[80:81], 0, v[2:3]
	s_mov_b32 s14, 0x7021000
	v_add_co_u32_e32 v80, vcc, s14, v80
	s_nop 1
	v_addc_co_u32_e32 v81, vcc, 0, v81, vcc
	global_load_dwordx4 v[60:63], v[80:81], off
	v_and_b32_e32 v54, 0xf8, v13
	v_lshlrev_b32_e32 v54, 2, v54
	global_load_dwordx4 v[84:87], v54, s[4:5] offset:16
	global_load_dwordx4 v[88:91], v54, s[4:5]
	v_add_u32_e32 v1, s2, v1
	v_lshl_add_u64 v[4:5], s[18:19], 0, v[4:5]
	s_waitcnt vmcnt(4)
	v_lshlrev_b32_e32 v6, 16, v14
	v_and_b32_e32 v7, 0xffff0000, v14
	v_lshlrev_b32_e32 v22, 16, v15
	v_and_b32_e32 v23, 0xffff0000, v15
	v_lshlrev_b32_e32 v24, 16, v16
	v_and_b32_e32 v25, 0xffff0000, v16
	v_lshlrev_b32_e32 v26, 16, v17
	v_and_b32_e32 v27, 0xffff0000, v17
	s_waitcnt vmcnt(3)
	v_lshlrev_b32_e32 v28, 16, v56
	v_and_b32_e32 v29, 0xffff0000, v56
	v_lshlrev_b32_e32 v30, 16, v57
	v_and_b32_e32 v31, 0xffff0000, v57
	v_lshlrev_b32_e32 v20, 16, v58
	v_and_b32_e32 v21, 0xffff0000, v58
	v_lshlrev_b32_e32 v32, 16, v59
	v_and_b32_e32 v33, 0xffff0000, v59
	v_pk_add_f32 v[24:25], v[24:25], v[20:21]
	v_pk_add_f32 v[6:7], v[6:7], v[28:29]
	v_pk_add_f32 v[22:23], v[22:23], v[30:31]
	v_pk_mul_f32 v[28:29], v[6:7], v[6:7]
	v_pk_mul_f32 v[30:31], v[22:23], v[22:23]
	v_add_f32_e32 v28, v28, v29
	v_add_f32_e32 v28, v28, v30
	v_pk_mul_f32 v[34:35], v[24:25], v[24:25]
	v_add_f32_e32 v28, v31, v28
	v_pk_add_f32 v[26:27], v[26:27], v[32:33]
	v_add_f32_e32 v28, v34, v28
	v_pk_mul_f32 v[32:33], v[26:27], v[26:27]
	v_add_f32_e32 v28, v35, v28
	v_add_f32_e32 v28, v32, v28
	v_add_f32_e32 v28, v33, v28
	s_nop 1
	v_add_f32_dpp v28, v28, v28 quad_perm:[1,0,3,2] row_mask:0xf bank_mask:0xf
	s_nop 1
	v_add_f32_dpp v28, v28, v28 quad_perm:[2,3,0,1] row_mask:0xf bank_mask:0xf
	s_nop 1
	v_add_f32_dpp v28, v28, v28 row_half_mirror row_mask:0xf bank_mask:0xf
	s_nop 1
	v_add_f32_dpp v28, v28, v28 row_mirror row_mask:0xf bank_mask:0xf
	v_mov_b32_e32 v29, v28
	s_nop 1
	v_permlane16_swap_b32 v28, v29
	v_add_f32_e32 v28, v28, v29
	v_fmamk_f32 v28, v28, 0x3b800000, v218
	v_mul_f32_e32 v29, 0x4b800000, v28
	s_waitcnt vmcnt(2)
	v_lshlrev_b32_e32 v37, 16, v60
	v_and_b32_e32 v44, 0xffff0000, v60
	v_lshlrev_b32_e32 v40, 16, v62
	v_and_b32_e32 v41, 0xffff0000, v62
	v_mul_f32_e32 v14, 0xbfb8aa3b, v40
	v_mul_f32_e32 v39, 0xbfb8aa3b, v41
	v_exp_f32_e32 v38, v14
	v_exp_f32_e32 v39, v39
	v_lshlrev_b32_e32 v42, 16, v61
	v_and_b32_e32 v43, 0xffff0000, v61
	v_lshlrev_b32_e32 v45, 16, v63
	v_pk_add_f32 v[38:39], v[38:39], 1.0 op_sel_hi:[1,0]
	v_and_b32_e32 v46, 0xffff0000, v63
	v_div_scale_f32 v47, s[14:15], v39, v39, v41
	v_rcp_f32_e32 v48, v47
	v_add_u32_e32 v13, s3, v13
	v_fma_f32 v49, -v47, v48, 1.0
	v_fmac_f32_e32 v48, v49, v48
	v_div_scale_f32 v49, vcc, v41, v39, v41
	v_mul_f32_e32 v50, v49, v48
	v_fma_f32 v51, -v47, v50, v49
	v_fmac_f32_e32 v50, v51, v48
	v_fma_f32 v47, -v47, v50, v49
	v_div_fmas_f32 v47, v47, v48, v50
	v_div_fixup_f32 v39, v47, v39, v41
	v_div_scale_f32 v41, s[14:15], v38, v38, v40
	v_rcp_f32_e32 v47, v41
	s_nop 0
	v_fma_f32 v48, -v41, v47, 1.0
	v_fmac_f32_e32 v47, v48, v47
	v_div_scale_f32 v48, vcc, v40, v38, v40
	v_mul_f32_e32 v49, v48, v47
	v_fma_f32 v50, -v41, v49, v48
	v_fmac_f32_e32 v49, v50, v47
	v_fma_f32 v41, -v41, v49, v48
	v_div_fmas_f32 v41, v41, v47, v49
	v_div_fixup_f32 v38, v41, v38, v40
	v_mul_f32_e32 v40, 0xbfb8aa3b, v42
	v_mul_f32_e32 v41, 0xbfb8aa3b, v43
	v_exp_f32_e32 v40, v40
	v_exp_f32_e32 v41, v41
	s_nop 0
	v_pk_add_f32 v[40:41], v[40:41], 1.0 op_sel_hi:[1,0]
	s_nop 0
	v_div_scale_f32 v47, s[14:15], v41, v41, v43
	v_rcp_f32_e32 v48, v47
	s_nop 0
	v_fma_f32 v49, -v47, v48, 1.0
	v_fmac_f32_e32 v48, v49, v48
	v_div_scale_f32 v49, vcc, v43, v41, v43
	v_mul_f32_e32 v50, v49, v48
	v_fma_f32 v51, -v47, v50, v49
	v_fmac_f32_e32 v50, v51, v48
	v_fma_f32 v47, -v47, v50, v49
	v_div_fmas_f32 v47, v47, v48, v50
	v_div_fixup_f32 v41, v47, v41, v43
	v_div_scale_f32 v43, s[14:15], v40, v40, v42
	v_rcp_f32_e32 v47, v43
	s_nop 0
	v_fma_f32 v48, -v43, v47, 1.0
	v_fmac_f32_e32 v47, v48, v47
	v_div_scale_f32 v48, vcc, v42, v40, v42
	v_mul_f32_e32 v49, v48, v47
	v_fma_f32 v50, -v43, v49, v48
	v_fmac_f32_e32 v49, v50, v47
	v_fma_f32 v43, -v43, v49, v48
	v_div_fmas_f32 v43, v43, v47, v49
	v_div_fixup_f32 v40, v43, v40, v42
	v_mul_f32_e32 v42, 0xbfb8aa3b, v37
	v_mul_f32_e32 v43, 0xbfb8aa3b, v44
	v_exp_f32_e32 v42, v42
	v_exp_f32_e32 v43, v43
	s_nop 0
	v_pk_add_f32 v[42:43], v[42:43], 1.0 op_sel_hi:[1,0]
	s_nop 0
	v_div_scale_f32 v47, s[14:15], v43, v43, v44
	v_rcp_f32_e32 v48, v47
	s_nop 0
	v_fma_f32 v49, -v47, v48, 1.0
	v_fmac_f32_e32 v48, v49, v48
	v_div_scale_f32 v49, vcc, v44, v43, v44
	v_mul_f32_e32 v50, v49, v48
	v_fma_f32 v51, -v47, v50, v49
	v_fmac_f32_e32 v50, v51, v48
	v_fma_f32 v47, -v47, v50, v49
	v_div_fmas_f32 v47, v47, v48, v50
	v_div_fixup_f32 v43, v47, v43, v44
	v_div_scale_f32 v44, s[14:15], v42, v42, v37
	v_rcp_f32_e32 v47, v44
	s_nop 0
	v_fma_f32 v48, -v44, v47, 1.0
	v_fmac_f32_e32 v47, v48, v47
	v_div_scale_f32 v48, vcc, v37, v42, v37
	v_mul_f32_e32 v49, v48, v47
	v_fma_f32 v50, -v44, v49, v48
	v_fmac_f32_e32 v49, v50, v47
	v_fma_f32 v44, -v44, v49, v48
	v_div_fmas_f32 v44, v44, v47, v49
	v_cmp_gt_f32_e32 vcc, s71, v28
	v_div_fixup_f32 v42, v44, v42, v37
	s_nop 0
	v_cndmask_b32_e32 v28, v28, v29, vcc
	v_rsq_f32_e32 v28, v28
	s_nop 0
	v_mul_f32_e32 v29, 0x45800000, v28
	v_cndmask_b32_e32 v28, v28, v29, vcc
	v_pk_mul_f32 v[6:7], v[6:7], v[28:29] op_sel_hi:[1,0]
	s_waitcnt vmcnt(0)
	v_mov_b64_e32 v[14:15], v[84:85]
	v_mov_b64_e32 v[16:17], v[86:87]
	v_mov_b64_e32 v[18:19], v[88:89]
	v_mov_b64_e32 v[20:21], v[90:91]
	v_pk_mul_f32 v[6:7], v[18:19], v[6:7]
	v_pk_mul_f32 v[18:19], v[22:23], v[28:29] op_sel_hi:[1,0]
	v_pk_mul_f32 v[22:23], v[26:27], v[28:29] op_sel_hi:[1,0]
	v_pk_mul_f32 v[18:19], v[20:21], v[18:19]
	v_pk_mul_f32 v[20:21], v[24:25], v[28:29] op_sel_hi:[1,0]
	v_pk_mul_f32 v[16:17], v[16:17], v[22:23]
	v_pk_mul_f32 v[14:15], v[14:15], v[20:21]
	v_mul_f32_e32 v20, 0xbfb8aa3b, v45
	v_mul_f32_e32 v21, 0xbfb8aa3b, v46
	v_exp_f32_e32 v20, v20
	v_exp_f32_e32 v21, v21
	v_pk_mul_f32 v[6:7], v[42:43], v[6:7]
	v_pk_mul_f32 v[18:19], v[40:41], v[18:19]
	v_pk_mul_f32 v[14:15], v[38:39], v[14:15]
	v_pk_add_f32 v[20:21], v[20:21], 1.0 op_sel_hi:[1,0]
	s_nop 0
	v_div_scale_f32 v22, s[14:15], v21, v21, v46
	v_rcp_f32_e32 v23, v22
	s_nop 0
	v_fma_f32 v24, -v22, v23, 1.0
	v_fmac_f32_e32 v23, v24, v23
	v_div_scale_f32 v24, vcc, v46, v21, v46
	v_mul_f32_e32 v25, v24, v23
	v_fma_f32 v26, -v22, v25, v24
	v_fmac_f32_e32 v25, v26, v23
	v_fma_f32 v22, -v22, v25, v24
	v_div_fmas_f32 v22, v22, v23, v25
	v_div_fixup_f32 v21, v22, v21, v46
	v_div_scale_f32 v22, s[14:15], v20, v20, v45
	v_rcp_f32_e32 v23, v22
	s_nop 0
	v_fma_f32 v24, -v22, v23, 1.0
	v_fmac_f32_e32 v23, v24, v23
	v_div_scale_f32 v24, vcc, v45, v20, v45
	v_mul_f32_e32 v25, v24, v23
	v_fma_f32 v26, -v22, v25, v24
	v_fmac_f32_e32 v25, v26, v23
	v_fma_f32 v22, -v22, v25, v24
	v_div_fmas_f32 v22, v22, v23, v25
	v_div_fixup_f32 v20, v22, v20, v45
	v_pk_mul_f32 v[16:17], v[20:21], v[16:17]
	v_cmp_lt_i32_e32 vcc, s17, v1
	v_lshl_add_u64 v[20:21], v[4:5], 0, v[2:3]
	v_cvt_pk_bf16_f32 v4, v6, v7
	v_cvt_pk_bf16_f32 v5, v18, v19
	v_cvt_pk_bf16_f32 v6, v14, v15
	v_cvt_pk_bf16_f32 v7, v16, v17
	s_or_b64 s[6:7], vcc, s[6:7]
	global_store_dwordx4 v[20:21], v[4:7], off
	s_andn2_b64 exec, exec, s[6:7]
	s_cbranch_execnz .LBB0_501

.LBB0_724:
	v_ashrrev_i32_e32 v2, 10, v1
	v_bfe_u32 v52, v1, 7, 13
	v_mov_b64_e32 v[4:5], s[34:35]
	v_and_b32_e32 v6, 0xfffffc00, v2
	v_bfe_u32 v51, v1, 3, 4
	v_mad_u64_u32 v[4:5], s[0:1], v52, s67, v[4:5]
	v_ashrrev_i32_e32 v7, 31, v6
	v_lshl_add_u64 v[4:5], v[6:7], 1, v[4:5]
	v_lshlrev_b32_e32 v2, 7, v51
	v_lshl_add_u64 v[4:5], v[4:5], 0, v[2:3]
	v_mov_b32_e32 v25, v3
	v_lshl_add_u64 v[4:5], v[4:5], 0, v[24:25]
	global_load_dwordx4 v[4:7], v[4:5], off
	v_cmp_gt_u32_e64 s[0:1], s43, v1
	v_mov_b32_e32 v2, 0x108
	v_mov_b32_e32 v8, 0x100
	v_cndmask_b32_e64 v2, v2, v8, s[0:1]
	v_lshl_add_u64 v[8:9], s[30:31], 0, v[2:3]
	global_load_dwordx2 v[26:27], v[8:9], off
	s_movk_i32 s3, 0x1000
	v_cndmask_b32_e64 v25, 1.0, v232, s[0:1]
	v_cmp_lt_u32_e64 s[0:1], s44, v1
	v_cmp_gt_u32_e64 s[4:5], s3, v52
	s_waitcnt vmcnt(0)
	v_lshlrev_b32_e32 v14, 16, v4
	v_and_b32_e32 v15, 0xffff0000, v4
	v_lshlrev_b32_e32 v32, 16, v5
	v_and_b32_e32 v33, 0xffff0000, v5
	v_pk_mul_f32 v[4:5], v[14:15], v[14:15]
	v_lshlrev_b32_e32 v28, 16, v6
	v_and_b32_e32 v29, 0xffff0000, v6
	v_lshlrev_b32_e32 v12, 16, v7
	v_and_b32_e32 v13, 0xffff0000, v7
	v_pk_mul_f32 v[6:7], v[32:33], v[32:33]
	v_add_f32_e32 v2, v4, v5
	v_add_f32_e32 v2, v2, v6
	v_pk_mul_f32 v[8:9], v[28:29], v[28:29]
	v_add_f32_e32 v2, v7, v2
	v_add_f32_e32 v2, v8, v2
	v_pk_mul_f32 v[10:11], v[12:13], v[12:13]
	v_add_f32_e32 v2, v9, v2
	v_add_f32_e32 v2, v10, v2
	v_add_f32_e32 v30, v11, v2
	v_lshlrev_b32_e32 v2, 2, v16
	s_and_saveexec_b64 s[12:13], s[4:5]
	s_xor_b64 s[12:13], exec, s[12:13]
	s_cbranch_execz .LBB0_726
	v_lshl_add_u64 v[8:9], v[26:27], 0, v[2:3]
	global_load_dwordx4 v[4:7], v[8:9], off
	s_nop 0
	global_load_dwordx4 v[8:11], v[8:9], off offset:16
	s_nop 1
	v_mov_b32_dpp v2, v30 quad_perm:[1,0,3,2] row_mask:0xf bank_mask:0xf
	s_waitcnt lgkmcnt(0)
	v_add_f32_e32 v2, v30, v2
	s_nop 1
	v_mov_b32_dpp v26, v2 quad_perm:[2,3,0,1] row_mask:0xf bank_mask:0xf
	s_waitcnt lgkmcnt(0)
	v_add_f32_e32 v2, v2, v26
	s_nop 1
	v_mov_b32_dpp v26, v2 row_half_mirror row_mask:0xf bank_mask:0xf
	s_waitcnt lgkmcnt(0)
	v_add_f32_e32 v2, v2, v26
	v_fmamk_f32 v2, v2, 0x3c800000, v218
	v_mul_f32_e32 v26, 0x4b800000, v2
	v_cmp_gt_f32_e64 s[4:5], s71, v2
	s_nop 1
	v_cndmask_b32_e64 v2, v2, v26, s[4:5]
	v_rsq_f32_e32 v2, v2
	s_nop 0
	v_mul_f32_e32 v26, 0x45800000, v2
	v_cndmask_b32_e64 v2, v2, v26, s[4:5]
	v_mul_f32_e32 v2, v25, v2
	s_waitcnt vmcnt(1)
	v_pk_mul_f32 v[26:27], v[4:5], v[2:3] op_sel_hi:[1,0]
	v_pk_mul_f32 v[30:31], v[6:7], v[2:3] op_sel_hi:[1,0]
	s_waitcnt vmcnt(0)
	v_pk_mul_f32 v[4:5], v[8:9], v[2:3] op_sel_hi:[1,0]
	v_pk_mul_f32 v[6:7], v[10:11], v[2:3] op_sel_hi:[1,0]
	v_pk_mul_f32 v[4:5], v[4:5], v[28:29]
	v_pk_mul_f32 v[6:7], v[6:7], v[12:13]
	v_pk_mul_f32 v[10:11], v[30:31], v[32:33]
	v_pk_mul_f32 v[8:9], v[26:27], v[14:15]
.LBB0_726:
	s_andn2_saveexec_b64 s[12:13], s[12:13]
	s_cbranch_execz .LBB0_728
	s_nop 4
	v_mov_b32_dpp v4, v30 quad_perm:[1,0,3,2] row_mask:0xf bank_mask:0xf
	v_lshl_add_u64 v[26:27], v[26:27], 0, v[2:3]
	v_bfe_u32 v2, v1, 7, 6
	s_waitcnt lgkmcnt(0)
	v_add_f32_e32 v4, v30, v4
	s_nop 1
	v_mov_b32_dpp v5, v4 quad_perm:[2,3,0,1] row_mask:0xf bank_mask:0xf
	s_waitcnt lgkmcnt(0)
	v_add_f32_e32 v4, v4, v5
	s_nop 1
	v_mov_b32_dpp v5, v4 row_half_mirror row_mask:0xf bank_mask:0xf
	s_waitcnt lgkmcnt(0)
	v_add_f32_e32 v4, v4, v5
	v_fmamk_f32 v4, v4, 0x3c800000, v218
	v_cmp_gt_f32_e64 s[4:5], s71, v4
	v_mul_f32_e32 v5, 0x4b800000, v4
	s_nop 0
	v_cndmask_b32_e64 v4, v4, v5, s[4:5]
	v_rsq_f32_e32 v4, v4
	s_nop 0
	v_mul_f32_e32 v5, 0x45800000, v4
	v_cndmask_b32_e64 v4, v4, v5, s[4:5]
	v_mul_f32_e32 v10, v25, v4
	v_bfe_u32 v4, v1, 13, 5
	v_cndmask_b32_e32 v2, v2, v4, vcc
	v_cvt_f32_ubyte0_e32 v2, v2
	v_and_b32_e32 v4, 2, v1
	v_cmp_eq_u32_e64 s[4:5], 0, v4
	v_mul_f32_e32 v4, v17, v2
	v_mul_f32_e32 v4, 0.15915494, v4
	v_cos_f32_e32 v8, v4
	v_sin_f32_e32 v30, v4
	v_mul_f32_e32 v4, v37, v2
	v_mul_f32_e32 v4, 0.15915494, v4
	v_cos_f32_e32 v9, v4
	v_sin_f32_e32 v31, v4
	global_load_dwordx4 v[4:7], v[26:27], off offset:16
	global_load_dwordx4 v[38:41], v[26:27], off
	s_waitcnt vmcnt(0)
	v_pk_mul_f32 v[26:27], v[38:39], v[10:11] op_sel_hi:[1,0]
	s_nop 0
	v_pk_mul_f32 v[14:15], v[26:27], v[14:15]
	s_nop 1
	v_mov_b32_dpp v26, v14 quad_perm:[2,3,0,1] row_mask:0xf bank_mask:0xf
	s_nop 1
	v_mov_b32_dpp v27, v15 quad_perm:[2,3,0,1] row_mask:0xf bank_mask:0xf
	v_mul_f32_e32 v11, v42, v2
	v_mul_f32_e32 v11, 0.15915494, v11
	v_sin_f32_e32 v34, v11
	s_waitcnt lgkmcnt(0)
	v_pk_mul_f32 v[26:27], v[30:31], v[26:27]
	v_cos_f32_e32 v30, v11
	v_mul_f32_e32 v11, v43, v2
	v_mul_f32_e32 v11, 0.15915494, v11
	v_pk_mul_f32 v[38:39], v[40:41], v[10:11] op_sel_hi:[1,0]
	v_sin_f32_e32 v35, v11
	v_pk_mul_f32 v[32:33], v[38:39], v[32:33]
	s_nop 1
	v_mov_b32_dpp v38, v32 quad_perm:[2,3,0,1] row_mask:0xf bank_mask:0xf
	s_nop 1
	v_mov_b32_dpp v39, v33 quad_perm:[2,3,0,1] row_mask:0xf bank_mask:0xf
	v_cos_f32_e32 v31, v11
	v_mul_f32_e32 v11, v44, v2
	v_mul_f32_e32 v11, 0.15915494, v11
	v_sin_f32_e32 v40, v11
	s_waitcnt lgkmcnt(0)
	v_pk_mul_f32 v[34:35], v[34:35], v[38:39]
	v_cos_f32_e32 v38, v11
	v_mul_f32_e32 v11, v45, v2
	v_mul_f32_e32 v11, 0.15915494, v11
	v_pk_mul_f32 v[4:5], v[4:5], v[10:11] op_sel_hi:[1,0]
	v_cos_f32_e32 v39, v11
	v_pk_mul_f32 v[4:5], v[4:5], v[28:29]
	s_nop 1
	v_mov_b32_dpp v28, v4 quad_perm:[2,3,0,1] row_mask:0xf bank_mask:0xf
	s_nop 1
	v_mov_b32_dpp v29, v5 quad_perm:[2,3,0,1] row_mask:0xf bank_mask:0xf
	v_sin_f32_e32 v41, v11
	v_mul_f32_e32 v11, v46, v2
	v_mul_f32_e32 v11, 0.15915494, v11
	v_pk_mul_f32 v[6:7], v[6:7], v[10:11] op_sel_hi:[1,0]
	v_mul_f32_e32 v2, v47, v2
	v_pk_mul_f32 v[6:7], v[6:7], v[12:13]
	s_waitcnt lgkmcnt(0)
	v_pk_mul_f32 v[28:29], v[40:41], v[28:29]
	v_cos_f32_e32 v40, v11
	v_sin_f32_e32 v54, v11
	v_mul_f32_e32 v2, 0.15915494, v2
	s_nop 1
	v_mov_b32_dpp v10, v6 quad_perm:[2,3,0,1] row_mask:0xf bank_mask:0xf
	s_nop 1
	v_mov_b32_dpp v11, v7 quad_perm:[2,3,0,1] row_mask:0xf bank_mask:0xf
	v_sin_f32_e32 v55, v2
	v_cos_f32_e32 v41, v2
	v_cndmask_b32_e64 v27, v27, -v27, s[4:5]
	v_cndmask_b32_e64 v26, v26, -v26, s[4:5]
	s_waitcnt lgkmcnt(0)
	v_pk_mul_f32 v[10:11], v[54:55], v[10:11]
	v_cndmask_b32_e64 v35, v35, -v35, s[4:5]
	v_cndmask_b32_e64 v34, v34, -v34, s[4:5]
	v_cndmask_b32_e64 v29, v29, -v29, s[4:5]
	v_cndmask_b32_e64 v28, v28, -v28, s[4:5]
	v_cndmask_b32_e64 v13, v11, -v11, s[4:5]
	v_cndmask_b32_e64 v12, v10, -v10, s[4:5]
	v_pk_fma_f32 v[8:9], v[8:9], v[14:15], v[26:27]
	v_pk_fma_f32 v[10:11], v[30:31], v[32:33], v[34:35]
	v_pk_fma_f32 v[4:5], v[38:39], v[4:5], v[28:29]
	v_pk_fma_f32 v[6:7], v[40:41], v[6:7], v[12:13]

.Lp0_loop:
	v_mov_b32_e32 v112, v1
	v_mov_b32_e32 v113, v15
	v_ashrrev_i32_e32 v2, 10, v1
	v_bfe_u32 v17, v1, 7, 13
	v_mov_b64_e32 v[4:5], s[34:35]
	v_and_b32_e32 v6, 0xfffffc00, v2
	v_bfe_u32 v16, v1, 3, 4
	v_mad_u64_u32 v[4:5], s[0:1], v17, s67, v[4:5]
	v_ashrrev_i32_e32 v7, 31, v6
	v_lshl_add_u64 v[4:5], v[6:7], 1, v[4:5]
	v_lshlrev_b32_e32 v2, 7, v16
	v_lshl_add_u64 v[4:5], v[4:5], 0, v[2:3]
	v_and_b32_e32 v2, 56, v15
	v_mov_b32_e32 v23, v3
	v_lshlrev_b32_e32 v22, 1, v2
	v_lshl_add_u64 v[4:5], v[4:5], 0, v[22:23]
	global_load_dwordx4 v[96:99], v[4:5], off
	v_add_u32_e32 v1, s2, v1
	v_add_u32_e32 v15, s3, v15
	v_ashrrev_i32_e32 v2, 10, v1
	v_bfe_u32 v17, v1, 7, 13
	v_mov_b64_e32 v[4:5], s[34:35]
	v_and_b32_e32 v6, 0xfffffc00, v2
	v_bfe_u32 v16, v1, 3, 4
	v_mad_u64_u32 v[4:5], s[0:1], v17, s67, v[4:5]
	v_ashrrev_i32_e32 v7, 31, v6
	v_lshl_add_u64 v[4:5], v[6:7], 1, v[4:5]
	v_lshlrev_b32_e32 v2, 7, v16
	v_lshl_add_u64 v[4:5], v[4:5], 0, v[2:3]
	v_and_b32_e32 v2, 56, v15
	v_mov_b32_e32 v23, v3
	v_lshlrev_b32_e32 v22, 1, v2
	v_lshl_add_u64 v[4:5], v[4:5], 0, v[22:23]
	global_load_dwordx4 v[100:103], v[4:5], off
	v_add_u32_e32 v1, s2, v1
	v_add_u32_e32 v15, s3, v15
	v_ashrrev_i32_e32 v2, 10, v1
	v_bfe_u32 v17, v1, 7, 13
	v_mov_b64_e32 v[4:5], s[34:35]
	v_and_b32_e32 v6, 0xfffffc00, v2
	v_bfe_u32 v16, v1, 3, 4
	v_mad_u64_u32 v[4:5], s[0:1], v17, s67, v[4:5]
	v_ashrrev_i32_e32 v7, 31, v6
	v_lshl_add_u64 v[4:5], v[6:7], 1, v[4:5]
	v_lshlrev_b32_e32 v2, 7, v16
	v_lshl_add_u64 v[4:5], v[4:5], 0, v[2:3]
	v_and_b32_e32 v2, 56, v15
	v_mov_b32_e32 v23, v3
	v_lshlrev_b32_e32 v22, 1, v2
	v_lshl_add_u64 v[4:5], v[4:5], 0, v[22:23]
	global_load_dwordx4 v[104:107], v[4:5], off
	v_add_u32_e32 v1, s2, v1
	v_add_u32_e32 v15, s3, v15
	v_ashrrev_i32_e32 v2, 10, v1
	v_bfe_u32 v17, v1, 7, 13
	v_mov_b64_e32 v[4:5], s[34:35]
	v_and_b32_e32 v6, 0xfffffc00, v2
	v_bfe_u32 v16, v1, 3, 4
	v_mad_u64_u32 v[4:5], s[0:1], v17, s67, v[4:5]
	v_ashrrev_i32_e32 v7, 31, v6
	v_lshl_add_u64 v[4:5], v[6:7], 1, v[4:5]
	v_lshlrev_b32_e32 v2, 7, v16
	v_lshl_add_u64 v[4:5], v[4:5], 0, v[2:3]
	v_and_b32_e32 v2, 56, v15
	v_mov_b32_e32 v23, v3
	v_lshlrev_b32_e32 v22, 1, v2
	v_lshl_add_u64 v[4:5], v[4:5], 0, v[22:23]
	global_load_dwordx4 v[108:111], v[4:5], off
	v_mov_b32_e32 v1, v112
	v_mov_b32_e32 v15, v113
	v_ashrrev_i32_e32 v2, 10, v1
	v_bfe_u32 v17, v1, 7, 13
	v_mov_b64_e32 v[4:5], s[34:35]
	v_and_b32_e32 v6, 0xfffffc00, v2
	v_bfe_u32 v16, v1, 3, 4
	v_mad_u64_u32 v[4:5], s[0:1], v17, s67, v[4:5]
	v_ashrrev_i32_e32 v7, 31, v6
	v_lshl_add_u64 v[4:5], v[6:7], 1, v[4:5]
	v_lshlrev_b32_e32 v2, 7, v16
	v_lshl_add_u64 v[4:5], v[4:5], 0, v[2:3]
	v_cmp_lt_u32_e32 vcc, s15, v1
	v_and_b32_e32 v2, 56, v15
	v_mov_b32_e32 v23, v3
	v_lshlrev_b32_e32 v22, 1, v2
	v_lshl_add_u64 v[4:5], v[4:5], 0, v[22:23]
	s_waitcnt vmcnt(3)
	v_mov_b64_e32 v[4:5], v[96:97]
	v_mov_b64_e32 v[6:7], v[98:99]
	v_lshlrev_b32_e32 v2, 2, v2
	v_mov_b32_e32 v37, 0xe8a0000
	s_movk_i32 s0, 0x1000
	v_cmp_gt_u32_e64 s[0:1], s0, v17
	v_cndmask_b32_e32 v8, v80, v88, vcc
	v_cndmask_b32_e32 v9, v81, v89, vcc
	v_cndmask_b32_e32 v10, v82, v90, vcc
	v_cndmask_b32_e32 v11, v83, v91, vcc
	v_cndmask_b32_e32 v18, v84, v92, vcc
	v_cndmask_b32_e32 v19, v85, v93, vcc
	v_cndmask_b32_e32 v20, v86, v94, vcc
	v_cndmask_b32_e32 v21, v87, v95, vcc
	v_lshlrev_b32_e32 v24, 16, v4
	v_and_b32_e32 v25, 0xffff0000, v4
	v_lshlrev_b32_e32 v4, 16, v5
	v_and_b32_e32 v5, 0xffff0000, v5
	v_pk_mul_f32 v[28:29], v[24:25], v[24:25]
	v_pk_mul_f32 v[30:31], v[4:5], v[4:5]
	v_add_f32_e32 v28, v28, v29
	v_lshlrev_b32_e32 v26, 16, v6
	v_and_b32_e32 v27, 0xffff0000, v6
	v_add_f32_e32 v28, v28, v30
	v_pk_mul_f32 v[32:33], v[26:27], v[26:27]
	v_add_f32_e32 v28, v31, v28
	v_lshlrev_b32_e32 v6, 16, v7
	v_and_b32_e32 v7, 0xffff0000, v7
	v_add_f32_e32 v28, v32, v28
	v_pk_mul_f32 v[34:35], v[6:7], v[6:7]
	v_add_f32_e32 v28, v33, v28
	v_add_f32_e32 v28, v34, v28
	v_add_f32_e32 v28, v35, v28
	s_nop 1
	v_mov_b32_dpp v30, v28 quad_perm:[1,0,3,2] row_mask:0xf bank_mask:0xf
	v_mov_b32_e32 v29, v3
	v_mov_b32_e32 v31, v3
	v_mov_b32_e32 v33, v3
	v_lshlrev_b32_e32 v32, 7, v17
	s_mov_b64 s[98:99], vcc
	v_and_b32_e32 v120, 31, v17
	v_lshlrev_b32_e32 v120, 5, v120
	v_and_b32_e32 v121, 0xffffffe0, v17
	v_lshl_or_b32 v120, v121, 7, v120
	v_bfe_u32 v121, v15, 4, 2
	v_lshl_or_b32 v120, v121, 10, v120
	v_bfe_u32 v121, v15, 3, 1
	v_lshl_or_b32 v120, v121, 4, v120
	v_cndmask_b32_e64 v32, v32, v120, s[98:99]
	s_waitcnt lgkmcnt(0)
	v_add_f32_e32 v28, v28, v30
	s_nop 1
	v_mov_b32_dpp v34, v28 quad_perm:[2,3,0,1] row_mask:0xf bank_mask:0xf
	v_lshlrev_b32_e32 v30, 20, v16
	v_cndmask_b32_e64 v17, v232, 1.0, vcc
	s_waitcnt lgkmcnt(0)
	v_add_f32_e32 v34, v28, v34
	s_nop 1
	v_mov_b32_dpp v35, v34 row_half_mirror row_mask:0xf bank_mask:0xf
	v_mov_b32_e32 v28, 0xd8a0000
	v_cndmask_b32_e32 v28, v28, v37, vcc
	v_lshl_add_u64 v[28:29], s[28:29], 0, v[28:29]
	v_lshl_add_u64 v[28:29], v[28:29], 0, v[30:31]
	s_waitcnt lgkmcnt(0)
	v_add_f32_e32 v34, v34, v35
	v_fmamk_f32 v34, v34, 0x3c800000, v218
	v_mul_f32_e32 v35, 0x4b800000, v34
	v_cmp_gt_f32_e64 s[4:5], s71, v34
	v_lshl_add_u64 v[28:29], v[28:29], 0, v[32:33]
	v_cndmask_b32_e64 v22, v22, v3, s[98:99]
	v_lshl_add_u64 v[22:23], v[28:29], 0, v[22:23]
	v_cndmask_b32_e64 v34, v34, v35, s[4:5]
	v_rsq_f32_e32 v34, v34
	s_nop 0
	v_mul_f32_e32 v28, 0x45800000, v34
	v_cndmask_b32_e64 v28, v34, v28, s[4:5]
	v_mul_f32_e32 v28, v17, v28
	s_and_b64 s[4:5], vcc, s[0:1]
	v_pk_mul_f32 v[8:9], v[8:9], v[28:29] op_sel_hi:[1,0]
	v_pk_mul_f32 v[10:11], v[10:11], v[28:29] op_sel_hi:[1,0]
	v_pk_mul_f32 v[18:19], v[18:19], v[28:29] op_sel_hi:[1,0]
	v_pk_mul_f32 v[20:21], v[20:21], v[28:29] op_sel_hi:[1,0]
	v_pk_mul_f32 v[8:9], v[8:9], v[24:25]
	v_pk_mul_f32 v[10:11], v[10:11], v[4:5]
	v_pk_mul_f32 v[4:5], v[18:19], v[26:27]
	v_pk_mul_f32 v[6:7], v[20:21], v[6:7]
	v_cvt_pk_bf16_f32 v18, v8, v9
	v_cvt_pk_bf16_f32 v19, v10, v11
	v_cvt_pk_bf16_f32 v20, v4, v5
	v_cvt_pk_bf16_f32 v21, v6, v7
	global_store_dwordx4 v[22:23], v[18:21], off
	s_and_saveexec_b64 s[0:1], s[4:5]
	s_cbranch_execz .Lp0_t0
	v_lshrrev_b32_e32 v17, 7, v1
	v_lshrrev_b32_e32 v18, 11, v1
	v_and_or_b32 v16, v18, s16, v16
	v_lshlrev_b32_e32 v17, 8, v17
	v_perm_b32 v16, v16, v17, s17
	v_mov_b32_e32 v17, v3
	v_lshl_add_u64 v[16:17], s[8:9], 0, v[16:17]
	v_lshl_add_u64 v[16:17], v[16:17], 0, v[2:3]
	global_store_dwordx4 v[16:17], v[8:11], off
	global_store_dwordx4 v[16:17], v[4:7], off offset:16
.Lp0_t0:
	s_or_b64 exec, exec, s[0:1]
	v_add_u32_e32 v1, s2, v1
	v_add_u32_e32 v15, s3, v15
	v_ashrrev_i32_e32 v2, 10, v1
	v_bfe_u32 v17, v1, 7, 13
	v_mov_b64_e32 v[4:5], s[34:35]
	v_and_b32_e32 v6, 0xfffffc00, v2
	v_bfe_u32 v16, v1, 3, 4
	v_mad_u64_u32 v[4:5], s[0:1], v17, s67, v[4:5]
	v_ashrrev_i32_e32 v7, 31, v6
	v_lshl_add_u64 v[4:5], v[6:7], 1, v[4:5]
	v_lshlrev_b32_e32 v2, 7, v16
	v_lshl_add_u64 v[4:5], v[4:5], 0, v[2:3]
	v_cmp_lt_u32_e32 vcc, s15, v1
	v_and_b32_e32 v2, 56, v15
	v_mov_b32_e32 v23, v3
	v_lshlrev_b32_e32 v22, 1, v2
	v_lshl_add_u64 v[4:5], v[4:5], 0, v[22:23]
	s_waitcnt vmcnt(3)
	v_mov_b64_e32 v[4:5], v[100:101]
	v_mov_b64_e32 v[6:7], v[102:103]
	v_lshlrev_b32_e32 v2, 2, v2
	v_mov_b32_e32 v37, 0xe8a0000
	s_movk_i32 s0, 0x1000
	v_cmp_gt_u32_e64 s[0:1], s0, v17
	v_cndmask_b32_e32 v8, v80, v88, vcc
	v_cndmask_b32_e32 v9, v81, v89, vcc
	v_cndmask_b32_e32 v10, v82, v90, vcc
	v_cndmask_b32_e32 v11, v83, v91, vcc
	v_cndmask_b32_e32 v18, v84, v92, vcc
	v_cndmask_b32_e32 v19, v85, v93, vcc
	v_cndmask_b32_e32 v20, v86, v94, vcc
	v_cndmask_b32_e32 v21, v87, v95, vcc
	v_lshlrev_b32_e32 v24, 16, v4
	v_and_b32_e32 v25, 0xffff0000, v4
	v_lshlrev_b32_e32 v4, 16, v5
	v_and_b32_e32 v5, 0xffff0000, v5
	v_pk_mul_f32 v[28:29], v[24:25], v[24:25]
	v_pk_mul_f32 v[30:31], v[4:5], v[4:5]
	v_add_f32_e32 v28, v28, v29
	v_lshlrev_b32_e32 v26, 16, v6
	v_and_b32_e32 v27, 0xffff0000, v6
	v_add_f32_e32 v28, v28, v30
	v_pk_mul_f32 v[32:33], v[26:27], v[26:27]
	v_add_f32_e32 v28, v31, v28
	v_lshlrev_b32_e32 v6, 16, v7
	v_and_b32_e32 v7, 0xffff0000, v7
	v_add_f32_e32 v28, v32, v28
	v_pk_mul_f32 v[34:35], v[6:7], v[6:7]
	v_add_f32_e32 v28, v33, v28
	v_add_f32_e32 v28, v34, v28
	v_add_f32_e32 v28, v35, v28
	s_nop 1
	v_mov_b32_dpp v30, v28 quad_perm:[1,0,3,2] row_mask:0xf bank_mask:0xf
	v_mov_b32_e32 v29, v3
	v_mov_b32_e32 v31, v3
	v_mov_b32_e32 v33, v3
	v_lshlrev_b32_e32 v32, 7, v17
	s_mov_b64 s[98:99], vcc
	v_and_b32_e32 v120, 31, v17
	v_lshlrev_b32_e32 v120, 5, v120
	v_and_b32_e32 v121, 0xffffffe0, v17
	v_lshl_or_b32 v120, v121, 7, v120
	v_bfe_u32 v121, v15, 4, 2
	v_lshl_or_b32 v120, v121, 10, v120
	v_bfe_u32 v121, v15, 3, 1
	v_lshl_or_b32 v120, v121, 4, v120
	v_cndmask_b32_e64 v32, v32, v120, s[98:99]
	s_waitcnt lgkmcnt(0)
	v_add_f32_e32 v28, v28, v30
	s_nop 1
	v_mov_b32_dpp v34, v28 quad_perm:[2,3,0,1] row_mask:0xf bank_mask:0xf
	v_lshlrev_b32_e32 v30, 20, v16
	v_cndmask_b32_e64 v17, v232, 1.0, vcc
	s_waitcnt lgkmcnt(0)
	v_add_f32_e32 v34, v28, v34
	s_nop 1
	v_mov_b32_dpp v35, v34 row_half_mirror row_mask:0xf bank_mask:0xf
	v_mov_b32_e32 v28, 0xd8a0000
	v_cndmask_b32_e32 v28, v28, v37, vcc
	v_lshl_add_u64 v[28:29], s[28:29], 0, v[28:29]
	v_lshl_add_u64 v[28:29], v[28:29], 0, v[30:31]
	s_waitcnt lgkmcnt(0)
	v_add_f32_e32 v34, v34, v35
	v_fmamk_f32 v34, v34, 0x3c800000, v218
	v_mul_f32_e32 v35, 0x4b800000, v34
	v_cmp_gt_f32_e64 s[4:5], s71, v34
	v_lshl_add_u64 v[28:29], v[28:29], 0, v[32:33]
	v_cndmask_b32_e64 v22, v22, v3, s[98:99]
	v_lshl_add_u64 v[22:23], v[28:29], 0, v[22:23]
	v_cndmask_b32_e64 v34, v34, v35, s[4:5]
	v_rsq_f32_e32 v34, v34
	s_nop 0
	v_mul_f32_e32 v28, 0x45800000, v34
	v_cndmask_b32_e64 v28, v34, v28, s[4:5]
	v_mul_f32_e32 v28, v17, v28
	s_and_b64 s[4:5], vcc, s[0:1]
	v_pk_mul_f32 v[8:9], v[8:9], v[28:29] op_sel_hi:[1,0]
	v_pk_mul_f32 v[10:11], v[10:11], v[28:29] op_sel_hi:[1,0]
	v_pk_mul_f32 v[18:19], v[18:19], v[28:29] op_sel_hi:[1,0]
	v_pk_mul_f32 v[20:21], v[20:21], v[28:29] op_sel_hi:[1,0]
	v_pk_mul_f32 v[8:9], v[8:9], v[24:25]
	v_pk_mul_f32 v[10:11], v[10:11], v[4:5]
	v_pk_mul_f32 v[4:5], v[18:19], v[26:27]
	v_pk_mul_f32 v[6:7], v[20:21], v[6:7]
	v_cvt_pk_bf16_f32 v18, v8, v9
	v_cvt_pk_bf16_f32 v19, v10, v11
	v_cvt_pk_bf16_f32 v20, v4, v5
	v_cvt_pk_bf16_f32 v21, v6, v7
	global_store_dwordx4 v[22:23], v[18:21], off
	s_and_saveexec_b64 s[0:1], s[4:5]
	s_cbranch_execz .Lp0_t1
	v_lshrrev_b32_e32 v17, 7, v1
	v_lshrrev_b32_e32 v18, 11, v1
	v_and_or_b32 v16, v18, s16, v16
	v_lshlrev_b32_e32 v17, 8, v17
	v_perm_b32 v16, v16, v17, s17
	v_mov_b32_e32 v17, v3
	v_lshl_add_u64 v[16:17], s[8:9], 0, v[16:17]
	v_lshl_add_u64 v[16:17], v[16:17], 0, v[2:3]
	global_store_dwordx4 v[16:17], v[8:11], off
	global_store_dwordx4 v[16:17], v[4:7], off offset:16
.Lp0_t1:
	s_or_b64 exec, exec, s[0:1]
	v_add_u32_e32 v1, s2, v1
	v_add_u32_e32 v15, s3, v15
	v_ashrrev_i32_e32 v2, 10, v1
	v_bfe_u32 v17, v1, 7, 13
	v_mov_b64_e32 v[4:5], s[34:35]
	v_and_b32_e32 v6, 0xfffffc00, v2
	v_bfe_u32 v16, v1, 3, 4
	v_mad_u64_u32 v[4:5], s[0:1], v17, s67, v[4:5]
	v_ashrrev_i32_e32 v7, 31, v6
	v_lshl_add_u64 v[4:5], v[6:7], 1, v[4:5]
	v_lshlrev_b32_e32 v2, 7, v16
	v_lshl_add_u64 v[4:5], v[4:5], 0, v[2:3]
	v_cmp_lt_u32_e32 vcc, s15, v1
	v_and_b32_e32 v2, 56, v15
	v_mov_b32_e32 v23, v3
	v_lshlrev_b32_e32 v22, 1, v2
	v_lshl_add_u64 v[4:5], v[4:5], 0, v[22:23]
	s_waitcnt vmcnt(3)
	v_mov_b64_e32 v[4:5], v[104:105]
	v_mov_b64_e32 v[6:7], v[106:107]
	v_lshlrev_b32_e32 v2, 2, v2
	v_mov_b32_e32 v37, 0xe8a0000
	s_movk_i32 s0, 0x1000
	v_cmp_gt_u32_e64 s[0:1], s0, v17
	v_cndmask_b32_e32 v8, v80, v88, vcc
	v_cndmask_b32_e32 v9, v81, v89, vcc
	v_cndmask_b32_e32 v10, v82, v90, vcc
	v_cndmask_b32_e32 v11, v83, v91, vcc
	v_cndmask_b32_e32 v18, v84, v92, vcc
	v_cndmask_b32_e32 v19, v85, v93, vcc
	v_cndmask_b32_e32 v20, v86, v94, vcc
	v_cndmask_b32_e32 v21, v87, v95, vcc
	v_lshlrev_b32_e32 v24, 16, v4
	v_and_b32_e32 v25, 0xffff0000, v4
	v_lshlrev_b32_e32 v4, 16, v5
	v_and_b32_e32 v5, 0xffff0000, v5
	v_pk_mul_f32 v[28:29], v[24:25], v[24:25]
	v_pk_mul_f32 v[30:31], v[4:5], v[4:5]
	v_add_f32_e32 v28, v28, v29
	v_lshlrev_b32_e32 v26, 16, v6
	v_and_b32_e32 v27, 0xffff0000, v6
	v_add_f32_e32 v28, v28, v30
	v_pk_mul_f32 v[32:33], v[26:27], v[26:27]
	v_add_f32_e32 v28, v31, v28
	v_lshlrev_b32_e32 v6, 16, v7
	v_and_b32_e32 v7, 0xffff0000, v7
	v_add_f32_e32 v28, v32, v28
	v_pk_mul_f32 v[34:35], v[6:7], v[6:7]
	v_add_f32_e32 v28, v33, v28
	v_add_f32_e32 v28, v34, v28
	v_add_f32_e32 v28, v35, v28
	s_nop 1
	v_mov_b32_dpp v30, v28 quad_perm:[1,0,3,2] row_mask:0xf bank_mask:0xf
	v_mov_b32_e32 v29, v3
	v_mov_b32_e32 v31, v3
	v_mov_b32_e32 v33, v3
	v_lshlrev_b32_e32 v32, 7, v17
	s_mov_b64 s[98:99], vcc
	v_and_b32_e32 v120, 31, v17
	v_lshlrev_b32_e32 v120, 5, v120
	v_and_b32_e32 v121, 0xffffffe0, v17
	v_lshl_or_b32 v120, v121, 7, v120
	v_bfe_u32 v121, v15, 4, 2
	v_lshl_or_b32 v120, v121, 10, v120
	v_bfe_u32 v121, v15, 3, 1
	v_lshl_or_b32 v120, v121, 4, v120
	v_cndmask_b32_e64 v32, v32, v120, s[98:99]
	s_waitcnt lgkmcnt(0)
	v_add_f32_e32 v28, v28, v30
	s_nop 1
	v_mov_b32_dpp v34, v28 quad_perm:[2,3,0,1] row_mask:0xf bank_mask:0xf
	v_lshlrev_b32_e32 v30, 20, v16
	v_cndmask_b32_e64 v17, v232, 1.0, vcc
	s_waitcnt lgkmcnt(0)
	v_add_f32_e32 v34, v28, v34
	s_nop 1
	v_mov_b32_dpp v35, v34 row_half_mirror row_mask:0xf bank_mask:0xf
	v_mov_b32_e32 v28, 0xd8a0000
	v_cndmask_b32_e32 v28, v28, v37, vcc
	v_lshl_add_u64 v[28:29], s[28:29], 0, v[28:29]
	v_lshl_add_u64 v[28:29], v[28:29], 0, v[30:31]
	s_waitcnt lgkmcnt(0)
	v_add_f32_e32 v34, v34, v35
	v_fmamk_f32 v34, v34, 0x3c800000, v218
	v_mul_f32_e32 v35, 0x4b800000, v34
	v_cmp_gt_f32_e64 s[4:5], s71, v34
	v_lshl_add_u64 v[28:29], v[28:29], 0, v[32:33]
	v_cndmask_b32_e64 v22, v22, v3, s[98:99]
	v_lshl_add_u64 v[22:23], v[28:29], 0, v[22:23]
	v_cndmask_b32_e64 v34, v34, v35, s[4:5]
	v_rsq_f32_e32 v34, v34
	s_nop 0
	v_mul_f32_e32 v28, 0x45800000, v34
	v_cndmask_b32_e64 v28, v34, v28, s[4:5]
	v_mul_f32_e32 v28, v17, v28
	s_and_b64 s[4:5], vcc, s[0:1]
	v_pk_mul_f32 v[8:9], v[8:9], v[28:29] op_sel_hi:[1,0]
	v_pk_mul_f32 v[10:11], v[10:11], v[28:29] op_sel_hi:[1,0]
	v_pk_mul_f32 v[18:19], v[18:19], v[28:29] op_sel_hi:[1,0]
	v_pk_mul_f32 v[20:21], v[20:21], v[28:29] op_sel_hi:[1,0]
	v_pk_mul_f32 v[8:9], v[8:9], v[24:25]
	v_pk_mul_f32 v[10:11], v[10:11], v[4:5]
	v_pk_mul_f32 v[4:5], v[18:19], v[26:27]
	v_pk_mul_f32 v[6:7], v[20:21], v[6:7]
	v_cvt_pk_bf16_f32 v18, v8, v9
	v_cvt_pk_bf16_f32 v19, v10, v11
	v_cvt_pk_bf16_f32 v20, v4, v5
	v_cvt_pk_bf16_f32 v21, v6, v7
	global_store_dwordx4 v[22:23], v[18:21], off
	s_and_saveexec_b64 s[0:1], s[4:5]
	s_cbranch_execz .Lp0_t2
	v_lshrrev_b32_e32 v17, 7, v1
	v_lshrrev_b32_e32 v18, 11, v1
	v_and_or_b32 v16, v18, s16, v16
	v_lshlrev_b32_e32 v17, 8, v17
	v_perm_b32 v16, v16, v17, s17
	v_mov_b32_e32 v17, v3
	v_lshl_add_u64 v[16:17], s[8:9], 0, v[16:17]
	v_lshl_add_u64 v[16:17], v[16:17], 0, v[2:3]
	global_store_dwordx4 v[16:17], v[8:11], off
	global_store_dwordx4 v[16:17], v[4:7], off offset:16
.Lp0_t2:
	s_or_b64 exec, exec, s[0:1]
	v_add_u32_e32 v1, s2, v1
	v_add_u32_e32 v15, s3, v15
	v_ashrrev_i32_e32 v2, 10, v1
	v_bfe_u32 v17, v1, 7, 13
	v_mov_b64_e32 v[4:5], s[34:35]
	v_and_b32_e32 v6, 0xfffffc00, v2
	v_bfe_u32 v16, v1, 3, 4
	v_mad_u64_u32 v[4:5], s[0:1], v17, s67, v[4:5]
	v_ashrrev_i32_e32 v7, 31, v6
	v_lshl_add_u64 v[4:5], v[6:7], 1, v[4:5]
	v_lshlrev_b32_e32 v2, 7, v16
	v_lshl_add_u64 v[4:5], v[4:5], 0, v[2:3]
	v_cmp_lt_u32_e32 vcc, s15, v1
	v_and_b32_e32 v2, 56, v15
	v_mov_b32_e32 v23, v3
	v_lshlrev_b32_e32 v22, 1, v2
	v_lshl_add_u64 v[4:5], v[4:5], 0, v[22:23]
	s_waitcnt vmcnt(3)
	v_mov_b64_e32 v[4:5], v[108:109]
	v_mov_b64_e32 v[6:7], v[110:111]
	v_lshlrev_b32_e32 v2, 2, v2
	v_mov_b32_e32 v37, 0xe8a0000
	s_movk_i32 s0, 0x1000
	v_cmp_gt_u32_e64 s[0:1], s0, v17
	v_cndmask_b32_e32 v8, v80, v88, vcc
	v_cndmask_b32_e32 v9, v81, v89, vcc
	v_cndmask_b32_e32 v10, v82, v90, vcc
	v_cndmask_b32_e32 v11, v83, v91, vcc
	v_cndmask_b32_e32 v18, v84, v92, vcc
	v_cndmask_b32_e32 v19, v85, v93, vcc
	v_cndmask_b32_e32 v20, v86, v94, vcc
	v_cndmask_b32_e32 v21, v87, v95, vcc
	v_lshlrev_b32_e32 v24, 16, v4
	v_and_b32_e32 v25, 0xffff0000, v4
	v_lshlrev_b32_e32 v4, 16, v5
	v_and_b32_e32 v5, 0xffff0000, v5
	v_pk_mul_f32 v[28:29], v[24:25], v[24:25]
	v_pk_mul_f32 v[30:31], v[4:5], v[4:5]
	v_add_f32_e32 v28, v28, v29
	v_lshlrev_b32_e32 v26, 16, v6
	v_and_b32_e32 v27, 0xffff0000, v6
	v_add_f32_e32 v28, v28, v30
	v_pk_mul_f32 v[32:33], v[26:27], v[26:27]
	v_add_f32_e32 v28, v31, v28
	v_lshlrev_b32_e32 v6, 16, v7
	v_and_b32_e32 v7, 0xffff0000, v7
	v_add_f32_e32 v28, v32, v28
	v_pk_mul_f32 v[34:35], v[6:7], v[6:7]
	v_add_f32_e32 v28, v33, v28
	v_add_f32_e32 v28, v34, v28
	v_add_f32_e32 v28, v35, v28
	s_nop 1
	v_mov_b32_dpp v30, v28 quad_perm:[1,0,3,2] row_mask:0xf bank_mask:0xf
	v_mov_b32_e32 v29, v3
	v_mov_b32_e32 v31, v3
	v_mov_b32_e32 v33, v3
	v_lshlrev_b32_e32 v32, 7, v17
	s_mov_b64 s[98:99], vcc
	v_and_b32_e32 v120, 31, v17
	v_lshlrev_b32_e32 v120, 5, v120
	v_and_b32_e32 v121, 0xffffffe0, v17
	v_lshl_or_b32 v120, v121, 7, v120
	v_bfe_u32 v121, v15, 4, 2
	v_lshl_or_b32 v120, v121, 10, v120
	v_bfe_u32 v121, v15, 3, 1
	v_lshl_or_b32 v120, v121, 4, v120
	v_cndmask_b32_e64 v32, v32, v120, s[98:99]
	s_waitcnt lgkmcnt(0)
	v_add_f32_e32 v28, v28, v30
	s_nop 1
	v_mov_b32_dpp v34, v28 quad_perm:[2,3,0,1] row_mask:0xf bank_mask:0xf
	v_lshlrev_b32_e32 v30, 20, v16
	v_cndmask_b32_e64 v17, v232, 1.0, vcc
	s_waitcnt lgkmcnt(0)
	v_add_f32_e32 v34, v28, v34
	s_nop 1
	v_mov_b32_dpp v35, v34 row_half_mirror row_mask:0xf bank_mask:0xf
	v_mov_b32_e32 v28, 0xd8a0000
	v_cndmask_b32_e32 v28, v28, v37, vcc
	v_lshl_add_u64 v[28:29], s[28:29], 0, v[28:29]
	v_lshl_add_u64 v[28:29], v[28:29], 0, v[30:31]
	s_waitcnt lgkmcnt(0)
	v_add_f32_e32 v34, v34, v35
	v_fmamk_f32 v34, v34, 0x3c800000, v218
	v_mul_f32_e32 v35, 0x4b800000, v34
	v_cmp_gt_f32_e64 s[4:5], s71, v34
	v_lshl_add_u64 v[28:29], v[28:29], 0, v[32:33]
	v_cndmask_b32_e64 v22, v22, v3, s[98:99]
	v_lshl_add_u64 v[22:23], v[28:29], 0, v[22:23]
	v_cndmask_b32_e64 v34, v34, v35, s[4:5]
	v_rsq_f32_e32 v34, v34
	s_nop 0
	v_mul_f32_e32 v28, 0x45800000, v34
	v_cndmask_b32_e64 v28, v34, v28, s[4:5]
	v_mul_f32_e32 v28, v17, v28
	s_and_b64 s[4:5], vcc, s[0:1]
	v_pk_mul_f32 v[8:9], v[8:9], v[28:29] op_sel_hi:[1,0]
	v_pk_mul_f32 v[10:11], v[10:11], v[28:29] op_sel_hi:[1,0]
	v_pk_mul_f32 v[18:19], v[18:19], v[28:29] op_sel_hi:[1,0]
	v_pk_mul_f32 v[20:21], v[20:21], v[28:29] op_sel_hi:[1,0]
	v_pk_mul_f32 v[8:9], v[8:9], v[24:25]
	v_pk_mul_f32 v[10:11], v[10:11], v[4:5]
	v_pk_mul_f32 v[4:5], v[18:19], v[26:27]
	v_pk_mul_f32 v[6:7], v[20:21], v[6:7]
	v_cvt_pk_bf16_f32 v18, v8, v9
	v_cvt_pk_bf16_f32 v19, v10, v11
	v_cvt_pk_bf16_f32 v20, v4, v5
	v_cvt_pk_bf16_f32 v21, v6, v7
	global_store_dwordx4 v[22:23], v[18:21], off
	s_and_saveexec_b64 s[0:1], s[4:5]
	s_cbranch_execz .Lp0_t3
	v_lshrrev_b32_e32 v17, 7, v1
	v_lshrrev_b32_e32 v18, 11, v1
	v_and_or_b32 v16, v18, s16, v16
	v_lshlrev_b32_e32 v17, 8, v17
	v_perm_b32 v16, v16, v17, s17
	v_mov_b32_e32 v17, v3
	v_lshl_add_u64 v[16:17], s[8:9], 0, v[16:17]
	v_lshl_add_u64 v[16:17], v[16:17], 0, v[2:3]
	global_store_dwordx4 v[16:17], v[8:11], off
	global_store_dwordx4 v[16:17], v[4:7], off offset:16

.Ln0_x:
	v_lshlrev_b32_e32 v2, 2, v22
	v_lshl_add_u64 v[4:5], v[4:5], 0, v[2:3]
	v_lshlrev_b64 v[18:19], 12, v[42:43]
	v_lshl_add_u64 v[6:7], v[24:25], 0, v[18:19]
	v_lshl_add_u64 v[8:9], v[26:27], 0, v[18:19]
	v_cmp_gt_i32_e32 vcc, s67, v20
	s_nop 1
	v_cndmask_b32_e64 v35, 2, 1, vcc
	v_cmp_lt_i32_e32 vcc, s27, v20
	s_nop 1
	v_cndmask_b32_e32 v35, 0, v35, vcc
	v_add_u32_e32 v35, s2, v35
	v_mul_i32_i24_e32 v18, 0x6000, v35
	v_ashrrev_i32_e32 v19, 31, v18
	v_lshl_add_u64 v[10:11], s[40:41], 0, v[18:19]
	v_lshl_add_u64 v[12:13], v[10:11], 0, v[2:3]
	s_mov_b64 s[0:1], 0x1000
	v_lshl_add_u64 v[14:15], v[12:13], 0, s[0:1]
	global_load_dwordx4 v[80:83], v[28:29], off
	global_load_dwordx4 v[84:87], v[28:29], off offset:1024
	global_load_dwordx4 v[88:91], v[28:29], off offset:2048
	global_load_dwordx4 v[92:95], v[28:29], off offset:3072
	global_load_dwordx4 v[96:99], v[12:13], off
	global_load_dwordx4 v[100:103], v[12:13], off offset:1024
	global_load_dwordx4 v[104:107], v[12:13], off offset:2048
	global_load_dwordx4 v[108:111], v[12:13], off offset:3072
	global_load_dwordx4 v[112:115], v[14:15], off
	global_load_dwordx4 v[116:119], v[14:15], off offset:1024
	global_load_dwordx4 v[120:123], v[14:15], off offset:2048
	global_load_dwordx4 v[124:127], v[14:15], off offset:3072
	s_and_b64 vcc, exec, s[12:13]
	s_cbranch_vccnz .Ln0_addp1
	global_load_dwordx4 v[188:191], v[4:5], off
	global_load_dwordx4 v[192:195], v[4:5], off offset:1024
	global_load_dwordx4 v[196:199], v[4:5], off offset:2048
	global_load_dwordx4 v[200:203], v[4:5], off offset:3072
	v_lshl_add_u64 v[4:5], v[4:5], 0, s[4:5]
	global_load_dwordx4 v[204:207], v[4:5], off
	global_load_dwordx4 v[208:211], v[4:5], off offset:1024
	global_load_dwordx4 v[212:215], v[4:5], off offset:2048
	global_load_dwordx4 v[234:237], v[4:5], off offset:3072
	v_lshl_add_u64 v[4:5], v[4:5], 0, s[4:5]
	global_load_dwordx4 v[238:241], v[4:5], off
	global_load_dwordx4 v[242:245], v[4:5], off offset:1024
	global_load_dwordx4 v[246:249], v[4:5], off offset:2048
	global_load_dwordx4 v[250:253], v[4:5], off offset:3072
	v_lshl_add_u64 v[4:5], v[4:5], 0, s[4:5]
	global_load_dwordx4 v[128:131], v[4:5], off
	global_load_dwordx4 v[132:135], v[4:5], off offset:1024
	global_load_dwordx4 v[136:139], v[4:5], off offset:2048
	global_load_dwordx4 v[142:145], v[4:5], off offset:3072
	s_waitcnt vmcnt(0)
	v_pk_mul_f32 v[18:19], v[188:189], v[188:189]
	v_pk_mul_f32 v[170:171], v[190:191], v[190:191]
	v_add_f32_e32 v44, v19, v18
	v_add_f32_e32 v44, v170, v44
	v_add_f32_e32 v44, v171, v44
	v_pk_mul_f32 v[18:19], v[192:193], v[192:193]
	v_pk_mul_f32 v[170:171], v[194:195], v[194:195]
	v_add_f32_e32 v45, v19, v18
	v_add_f32_e32 v45, v170, v45
	v_add_f32_e32 v45, v171, v45
	v_pk_mul_f32 v[18:19], v[196:197], v[196:197]
	v_pk_mul_f32 v[170:171], v[198:199], v[198:199]
	v_add_f32_e32 v46, v19, v18
	v_add_f32_e32 v46, v170, v46
	v_add_f32_e32 v46, v171, v46
	v_pk_mul_f32 v[18:19], v[200:201], v[200:201]
	v_pk_mul_f32 v[170:171], v[202:203], v[202:203]
	v_add_f32_e32 v47, v19, v18
	v_add_f32_e32 v47, v170, v47
	v_add_f32_e32 v47, v171, v47
	v_add_f32_e32 v158, v44, v45
	v_add_f32_e32 v158, v158, v46
	v_add_f32_e32 v158, v158, v47
	v_pk_mul_f32 v[18:19], v[204:205], v[204:205]
	v_pk_mul_f32 v[170:171], v[206:207], v[206:207]
	v_add_f32_e32 v44, v19, v18
	v_add_f32_e32 v44, v170, v44
	v_add_f32_e32 v44, v171, v44
	v_pk_mul_f32 v[18:19], v[208:209], v[208:209]
	v_pk_mul_f32 v[170:171], v[210:211], v[210:211]
	v_add_f32_e32 v45, v19, v18
	v_add_f32_e32 v45, v170, v45
	v_add_f32_e32 v45, v171, v45
	v_pk_mul_f32 v[18:19], v[212:213], v[212:213]
	v_pk_mul_f32 v[170:171], v[214:215], v[214:215]
	v_add_f32_e32 v46, v19, v18
	v_add_f32_e32 v46, v170, v46
	v_add_f32_e32 v46, v171, v46
	v_pk_mul_f32 v[18:19], v[234:235], v[234:235]
	v_pk_mul_f32 v[170:171], v[236:237], v[236:237]
	v_add_f32_e32 v47, v19, v18
	v_add_f32_e32 v47, v170, v47
	v_add_f32_e32 v47, v171, v47
	v_add_f32_e32 v160, v44, v45
	v_add_f32_e32 v160, v160, v46
	v_add_f32_e32 v160, v160, v47
	v_pk_mul_f32 v[18:19], v[238:239], v[238:239]
	v_pk_mul_f32 v[170:171], v[240:241], v[240:241]
	v_add_f32_e32 v44, v19, v18
	v_add_f32_e32 v44, v170, v44
	v_add_f32_e32 v44, v171, v44
	v_pk_mul_f32 v[18:19], v[242:243], v[242:243]
	v_pk_mul_f32 v[170:171], v[244:245], v[244:245]
	v_add_f32_e32 v45, v19, v18
	v_add_f32_e32 v45, v170, v45
	v_add_f32_e32 v45, v171, v45
	v_pk_mul_f32 v[18:19], v[246:247], v[246:247]
	v_pk_mul_f32 v[170:171], v[248:249], v[248:249]
	v_add_f32_e32 v46, v19, v18
	v_add_f32_e32 v46, v170, v46
	v_add_f32_e32 v46, v171, v46
	v_pk_mul_f32 v[18:19], v[250:251], v[250:251]
	v_pk_mul_f32 v[170:171], v[252:253], v[252:253]
	v_add_f32_e32 v47, v19, v18
	v_add_f32_e32 v47, v170, v47
	v_add_f32_e32 v47, v171, v47
	v_add_f32_e32 v162, v44, v45
	v_add_f32_e32 v162, v162, v46
	v_add_f32_e32 v162, v162, v47
	v_pk_mul_f32 v[18:19], v[128:129], v[128:129]
	v_pk_mul_f32 v[170:171], v[130:131], v[130:131]
	v_add_f32_e32 v44, v19, v18
	v_add_f32_e32 v44, v170, v44
	v_add_f32_e32 v44, v171, v44
	v_pk_mul_f32 v[18:19], v[132:133], v[132:133]
	v_pk_mul_f32 v[170:171], v[134:135], v[134:135]
	v_add_f32_e32 v45, v19, v18
	v_add_f32_e32 v45, v170, v45
	v_add_f32_e32 v45, v171, v45
	v_pk_mul_f32 v[18:19], v[136:137], v[136:137]
	v_pk_mul_f32 v[170:171], v[138:139], v[138:139]
	v_add_f32_e32 v46, v19, v18
	v_add_f32_e32 v46, v170, v46
	v_add_f32_e32 v46, v171, v46
	v_pk_mul_f32 v[18:19], v[142:143], v[142:143]
	v_pk_mul_f32 v[170:171], v[144:145], v[144:145]
	v_add_f32_e32 v47, v19, v18
	v_add_f32_e32 v47, v170, v47
	v_add_f32_e32 v47, v171, v47
	v_add_f32_e32 v164, v44, v45
	v_add_f32_e32 v164, v164, v46
	v_add_f32_e32 v164, v164, v47
	s_nop 1
	v_add_f32_dpp v158, v158, v158 quad_perm:[1,0,3,2] row_mask:0xf bank_mask:0xf
	v_add_f32_dpp v160, v160, v160 quad_perm:[1,0,3,2] row_mask:0xf bank_mask:0xf
	v_add_f32_dpp v162, v162, v162 quad_perm:[1,0,3,2] row_mask:0xf bank_mask:0xf
	v_add_f32_dpp v164, v164, v164 quad_perm:[1,0,3,2] row_mask:0xf bank_mask:0xf
	v_add_f32_dpp v158, v158, v158 quad_perm:[2,3,0,1] row_mask:0xf bank_mask:0xf
	v_add_f32_dpp v160, v160, v160 quad_perm:[2,3,0,1] row_mask:0xf bank_mask:0xf
	v_add_f32_dpp v162, v162, v162 quad_perm:[2,3,0,1] row_mask:0xf bank_mask:0xf
	v_add_f32_dpp v164, v164, v164 quad_perm:[2,3,0,1] row_mask:0xf bank_mask:0xf
	v_add_f32_dpp v158, v158, v158 row_half_mirror row_mask:0xf bank_mask:0xf
	v_add_f32_dpp v160, v160, v160 row_half_mirror row_mask:0xf bank_mask:0xf
	v_add_f32_dpp v162, v162, v162 row_half_mirror row_mask:0xf bank_mask:0xf
	v_add_f32_dpp v164, v164, v164 row_half_mirror row_mask:0xf bank_mask:0xf
	v_add_f32_dpp v158, v158, v158 row_mirror row_mask:0xf bank_mask:0xf
	v_add_f32_dpp v160, v160, v160 row_mirror row_mask:0xf bank_mask:0xf
	v_add_f32_dpp v162, v162, v162 row_mirror row_mask:0xf bank_mask:0xf
	v_add_f32_dpp v164, v164, v164 row_mirror row_mask:0xf bank_mask:0xf
	v_mov_b32_e32 v166, v158
	v_mov_b32_e32 v167, v160
	v_mov_b32_e32 v168, v162
	v_mov_b32_e32 v169, v164
	v_permlane16_swap_b32 v158, v166
	v_permlane16_swap_b32 v160, v167
	v_permlane16_swap_b32 v162, v168
	v_permlane16_swap_b32 v164, v169
	v_add_f32_e32 v158, v158, v166
	v_add_f32_e32 v160, v160, v167
	v_add_f32_e32 v162, v162, v168
	v_add_f32_e32 v164, v164, v169
	v_mov_b32_e32 v166, v158
	v_mov_b32_e32 v167, v160
	v_mov_b32_e32 v168, v162
	v_mov_b32_e32 v169, v164
	v_permlane32_swap_b32 v158, v166
	v_permlane32_swap_b32 v160, v167
	v_permlane32_swap_b32 v162, v168
	v_permlane32_swap_b32 v164, v169
	v_add_f32_e32 v158, v158, v166
	v_add_f32_e32 v160, v160, v167
	v_add_f32_e32 v162, v162, v168
	v_add_f32_e32 v164, v164, v169
	v_pk_add_f32 v[112:113], v[112:113], 1.0 op_sel_hi:[1,0]
	v_pk_add_f32 v[114:115], v[114:115], 1.0 op_sel_hi:[1,0]
	v_pk_add_f32 v[116:117], v[116:117], 1.0 op_sel_hi:[1,0]
	v_pk_add_f32 v[118:119], v[118:119], 1.0 op_sel_hi:[1,0]
	v_pk_add_f32 v[120:121], v[120:121], 1.0 op_sel_hi:[1,0]
	v_pk_add_f32 v[122:123], v[122:123], 1.0 op_sel_hi:[1,0]
	v_pk_add_f32 v[124:125], v[124:125], 1.0 op_sel_hi:[1,0]
	v_pk_add_f32 v[126:127], v[126:127], 1.0 op_sel_hi:[1,0]
	v_fmamk_f32 v158, v158, 0x3a800000, v218
	v_mul_f32_e32 v170, 0x4b800000, v158
	v_cmp_gt_f32_e32 vcc, s71, v158
	s_nop 1
	v_cndmask_b32_e32 v158, v158, v170, vcc
	v_rsq_f32_e32 v158, v158
	s_nop 0
	v_mul_f32_e32 v170, 0x45800000, v158
	v_cndmask_b32_e32 v158, v158, v170, vcc
	v_fmamk_f32 v160, v160, 0x3a800000, v218
	v_mul_f32_e32 v170, 0x4b800000, v160
	v_cmp_gt_f32_e32 vcc, s71, v160
	s_nop 1
	v_cndmask_b32_e32 v160, v160, v170, vcc
	v_rsq_f32_e32 v160, v160
	s_nop 0
	v_mul_f32_e32 v170, 0x45800000, v160
	v_cndmask_b32_e32 v160, v160, v170, vcc
	v_fmamk_f32 v162, v162, 0x3a800000, v218
	v_mul_f32_e32 v170, 0x4b800000, v162
	v_cmp_gt_f32_e32 vcc, s71, v162
	s_nop 1
	v_cndmask_b32_e32 v162, v162, v170, vcc
	v_rsq_f32_e32 v162, v162
	s_nop 0
	v_mul_f32_e32 v170, 0x45800000, v162
	v_cndmask_b32_e32 v162, v162, v170, vcc
	v_fmamk_f32 v164, v164, 0x3a800000, v218
	v_mul_f32_e32 v170, 0x4b800000, v164
	v_cmp_gt_f32_e32 vcc, s71, v164
	s_nop 1
	v_cndmask_b32_e32 v164, v164, v170, vcc
	v_rsq_f32_e32 v164, v164
	s_nop 0
	v_mul_f32_e32 v170, 0x45800000, v164
	v_cndmask_b32_e32 v164, v164, v170, vcc
	s_mov_b64 s[18:19], 0x800
	v_lshlrev_b64 v[16:17], 11, v[42:43]
	v_lshl_add_u64 v[16:17], v[30:31], 0, v[16:17]
	v_pk_mul_f32 v[188:189], v[188:189], v[158:159] op_sel_hi:[1,0]
	v_pk_mul_f32 v[188:189], v[80:81], v[188:189]
	v_pk_fma_f32 v[188:189], v[112:113], v[188:189], v[96:97]
	v_pk_mul_f32 v[190:191], v[190:191], v[158:159] op_sel_hi:[1,0]
	v_pk_mul_f32 v[190:191], v[82:83], v[190:191]
	v_pk_fma_f32 v[190:191], v[114:115], v[190:191], v[98:99]
	v_cvt_pk_bf16_f32 v188, v188, v189
	v_cvt_pk_bf16_f32 v189, v190, v191
	global_store_dwordx2 v[16:17], v[188:189], off
	v_pk_mul_f32 v[192:193], v[192:193], v[158:159] op_sel_hi:[1,0]
	v_pk_mul_f32 v[192:193], v[84:85], v[192:193]
	v_pk_fma_f32 v[192:193], v[116:117], v[192:193], v[100:101]
	v_pk_mul_f32 v[194:195], v[194:195], v[158:159] op_sel_hi:[1,0]
	v_pk_mul_f32 v[194:195], v[86:87], v[194:195]
	v_pk_fma_f32 v[194:195], v[118:119], v[194:195], v[102:103]
	v_cvt_pk_bf16_f32 v192, v192, v193
	v_cvt_pk_bf16_f32 v193, v194, v195
	global_store_dwordx2 v[16:17], v[192:193], off offset:512
	v_pk_mul_f32 v[196:197], v[196:197], v[158:159] op_sel_hi:[1,0]
	v_pk_mul_f32 v[196:197], v[88:89], v[196:197]
	v_pk_fma_f32 v[196:197], v[120:121], v[196:197], v[104:105]
	v_pk_mul_f32 v[198:199], v[198:199], v[158:159] op_sel_hi:[1,0]
	v_pk_mul_f32 v[198:199], v[90:91], v[198:199]
	v_pk_fma_f32 v[198:199], v[122:123], v[198:199], v[106:107]
	v_cvt_pk_bf16_f32 v196, v196, v197
	v_cvt_pk_bf16_f32 v197, v198, v199
	global_store_dwordx2 v[16:17], v[196:197], off offset:1024
	v_pk_mul_f32 v[200:201], v[200:201], v[158:159] op_sel_hi:[1,0]
	v_pk_mul_f32 v[200:201], v[92:93], v[200:201]
	v_pk_fma_f32 v[200:201], v[124:125], v[200:201], v[108:109]
	v_pk_mul_f32 v[202:203], v[202:203], v[158:159] op_sel_hi:[1,0]
	v_pk_mul_f32 v[202:203], v[94:95], v[202:203]
	v_pk_fma_f32 v[202:203], v[126:127], v[202:203], v[110:111]
	v_cvt_pk_bf16_f32 v200, v200, v201
	v_cvt_pk_bf16_f32 v201, v202, v203
	global_store_dwordx2 v[16:17], v[200:201], off offset:1536
	v_lshl_add_u64 v[16:17], v[16:17], 0, s[18:19]
	v_pk_mul_f32 v[204:205], v[204:205], v[160:161] op_sel_hi:[1,0]
	v_pk_mul_f32 v[204:205], v[80:81], v[204:205]
	v_pk_fma_f32 v[204:205], v[112:113], v[204:205], v[96:97]
	v_pk_mul_f32 v[206:207], v[206:207], v[160:161] op_sel_hi:[1,0]
	v_pk_mul_f32 v[206:207], v[82:83], v[206:207]
	v_pk_fma_f32 v[206:207], v[114:115], v[206:207], v[98:99]
	v_cvt_pk_bf16_f32 v204, v204, v205
	v_cvt_pk_bf16_f32 v205, v206, v207
	global_store_dwordx2 v[16:17], v[204:205], off
	v_pk_mul_f32 v[208:209], v[208:209], v[160:161] op_sel_hi:[1,0]
	v_pk_mul_f32 v[208:209], v[84:85], v[208:209]
	v_pk_fma_f32 v[208:209], v[116:117], v[208:209], v[100:101]
	v_pk_mul_f32 v[210:211], v[210:211], v[160:161] op_sel_hi:[1,0]
	v_pk_mul_f32 v[210:211], v[86:87], v[210:211]
	v_pk_fma_f32 v[210:211], v[118:119], v[210:211], v[102:103]
	v_cvt_pk_bf16_f32 v208, v208, v209
	v_cvt_pk_bf16_f32 v209, v210, v211
	global_store_dwordx2 v[16:17], v[208:209], off offset:512
	v_pk_mul_f32 v[212:213], v[212:213], v[160:161] op_sel_hi:[1,0]
	v_pk_mul_f32 v[212:213], v[88:89], v[212:213]
	v_pk_fma_f32 v[212:213], v[120:121], v[212:213], v[104:105]
	v_pk_mul_f32 v[214:215], v[214:215], v[160:161] op_sel_hi:[1,0]
	v_pk_mul_f32 v[214:215], v[90:91], v[214:215]
	v_pk_fma_f32 v[214:215], v[122:123], v[214:215], v[106:107]
	v_cvt_pk_bf16_f32 v212, v212, v213
	v_cvt_pk_bf16_f32 v213, v214, v215
	global_store_dwordx2 v[16:17], v[212:213], off offset:1024
	v_pk_mul_f32 v[234:235], v[234:235], v[160:161] op_sel_hi:[1,0]
	v_pk_mul_f32 v[234:235], v[92:93], v[234:235]
	v_pk_fma_f32 v[234:235], v[124:125], v[234:235], v[108:109]
	v_pk_mul_f32 v[236:237], v[236:237], v[160:161] op_sel_hi:[1,0]
	v_pk_mul_f32 v[236:237], v[94:95], v[236:237]
	v_pk_fma_f32 v[236:237], v[126:127], v[236:237], v[110:111]
	v_cvt_pk_bf16_f32 v234, v234, v235
	v_cvt_pk_bf16_f32 v235, v236, v237
	global_store_dwordx2 v[16:17], v[234:235], off offset:1536
	v_lshl_add_u64 v[16:17], v[16:17], 0, s[18:19]
	v_pk_mul_f32 v[238:239], v[238:239], v[162:163] op_sel_hi:[1,0]
	v_pk_mul_f32 v[238:239], v[80:81], v[238:239]
	v_pk_fma_f32 v[238:239], v[112:113], v[238:239], v[96:97]
	v_pk_mul_f32 v[240:241], v[240:241], v[162:163] op_sel_hi:[1,0]
	v_pk_mul_f32 v[240:241], v[82:83], v[240:241]
	v_pk_fma_f32 v[240:241], v[114:115], v[240:241], v[98:99]
	v_cvt_pk_bf16_f32 v238, v238, v239
	v_cvt_pk_bf16_f32 v239, v240, v241
	global_store_dwordx2 v[16:17], v[238:239], off
	v_pk_mul_f32 v[242:243], v[242:243], v[162:163] op_sel_hi:[1,0]
	v_pk_mul_f32 v[242:243], v[84:85], v[242:243]
	v_pk_fma_f32 v[242:243], v[116:117], v[242:243], v[100:101]
	v_pk_mul_f32 v[244:245], v[244:245], v[162:163] op_sel_hi:[1,0]
	v_pk_mul_f32 v[244:245], v[86:87], v[244:245]
	v_pk_fma_f32 v[244:245], v[118:119], v[244:245], v[102:103]
	v_cvt_pk_bf16_f32 v242, v242, v243
	v_cvt_pk_bf16_f32 v243, v244, v245
	global_store_dwordx2 v[16:17], v[242:243], off offset:512
	v_pk_mul_f32 v[246:247], v[246:247], v[162:163] op_sel_hi:[1,0]
	v_pk_mul_f32 v[246:247], v[88:89], v[246:247]
	v_pk_fma_f32 v[246:247], v[120:121], v[246:247], v[104:105]
	v_pk_mul_f32 v[248:249], v[248:249], v[162:163] op_sel_hi:[1,0]
	v_pk_mul_f32 v[248:249], v[90:91], v[248:249]
	v_pk_fma_f32 v[248:249], v[122:123], v[248:249], v[106:107]
	v_cvt_pk_bf16_f32 v246, v246, v247
	v_cvt_pk_bf16_f32 v247, v248, v249
	global_store_dwordx2 v[16:17], v[246:247], off offset:1024
	v_pk_mul_f32 v[250:251], v[250:251], v[162:163] op_sel_hi:[1,0]
	v_pk_mul_f32 v[250:251], v[92:93], v[250:251]
	v_pk_fma_f32 v[250:251], v[124:125], v[250:251], v[108:109]
	v_pk_mul_f32 v[252:253], v[252:253], v[162:163] op_sel_hi:[1,0]
	v_pk_mul_f32 v[252:253], v[94:95], v[252:253]
	v_pk_fma_f32 v[252:253], v[126:127], v[252:253], v[110:111]
	v_cvt_pk_bf16_f32 v250, v250, v251
	v_cvt_pk_bf16_f32 v251, v252, v253
	global_store_dwordx2 v[16:17], v[250:251], off offset:1536
	v_lshl_add_u64 v[16:17], v[16:17], 0, s[18:19]
	v_pk_mul_f32 v[128:129], v[128:129], v[164:165] op_sel_hi:[1,0]
	v_pk_mul_f32 v[128:129], v[80:81], v[128:129]
	v_pk_fma_f32 v[128:129], v[112:113], v[128:129], v[96:97]
	v_pk_mul_f32 v[130:131], v[130:131], v[164:165] op_sel_hi:[1,0]
	v_pk_mul_f32 v[130:131], v[82:83], v[130:131]
	v_pk_fma_f32 v[130:131], v[114:115], v[130:131], v[98:99]
	v_cvt_pk_bf16_f32 v128, v128, v129
	v_cvt_pk_bf16_f32 v129, v130, v131
	global_store_dwordx2 v[16:17], v[128:129], off
	v_pk_mul_f32 v[132:133], v[132:133], v[164:165] op_sel_hi:[1,0]
	v_pk_mul_f32 v[132:133], v[84:85], v[132:133]
	v_pk_fma_f32 v[132:133], v[116:117], v[132:133], v[100:101]
	v_pk_mul_f32 v[134:135], v[134:135], v[164:165] op_sel_hi:[1,0]
	v_pk_mul_f32 v[134:135], v[86:87], v[134:135]
	v_pk_fma_f32 v[134:135], v[118:119], v[134:135], v[102:103]
	v_cvt_pk_bf16_f32 v132, v132, v133
	v_cvt_pk_bf16_f32 v133, v134, v135
	global_store_dwordx2 v[16:17], v[132:133], off offset:512
	v_pk_mul_f32 v[136:137], v[136:137], v[164:165] op_sel_hi:[1,0]
	v_pk_mul_f32 v[136:137], v[88:89], v[136:137]
	v_pk_fma_f32 v[136:137], v[120:121], v[136:137], v[104:105]
	v_pk_mul_f32 v[138:139], v[138:139], v[164:165] op_sel_hi:[1,0]
	v_pk_mul_f32 v[138:139], v[90:91], v[138:139]
	v_pk_fma_f32 v[138:139], v[122:123], v[138:139], v[106:107]
	v_cvt_pk_bf16_f32 v136, v136, v137
	v_cvt_pk_bf16_f32 v137, v138, v139
	global_store_dwordx2 v[16:17], v[136:137], off offset:1024
	v_pk_mul_f32 v[142:143], v[142:143], v[164:165] op_sel_hi:[1,0]
	v_pk_mul_f32 v[142:143], v[92:93], v[142:143]
	v_pk_fma_f32 v[142:143], v[124:125], v[142:143], v[108:109]
	v_pk_mul_f32 v[144:145], v[144:145], v[164:165] op_sel_hi:[1,0]
	v_pk_mul_f32 v[144:145], v[94:95], v[144:145]
	v_pk_fma_f32 v[144:145], v[126:127], v[144:145], v[110:111]
	v_cvt_pk_bf16_f32 v142, v142, v143
	v_cvt_pk_bf16_f32 v143, v144, v145
	global_store_dwordx2 v[16:17], v[142:143], off offset:1536
	s_branch .LBB0_869
.Ln0_addp1:
	global_load_dwordx4 v[188:191], v[4:5], off
	global_load_dwordx4 v[192:195], v[4:5], off offset:1024
	global_load_dwordx4 v[196:199], v[4:5], off offset:2048
	global_load_dwordx4 v[200:203], v[4:5], off offset:3072
	global_load_dwordx4 v[52:55], v[6:7], off
	global_load_dwordx4 v[56:59], v[6:7], off offset:1024
	global_load_dwordx4 v[60:63], v[6:7], off offset:2048
	global_load_dwordx4 v[64:67], v[6:7], off offset:3072
	v_lshl_add_u64 v[4:5], v[4:5], 0, s[4:5]
	global_load_dwordx4 v[204:207], v[4:5], off
	global_load_dwordx4 v[208:211], v[4:5], off offset:1024
	global_load_dwordx4 v[212:215], v[4:5], off offset:2048
	global_load_dwordx4 v[234:237], v[4:5], off offset:3072
	v_lshl_add_u64 v[6:7], v[6:7], 0, s[4:5]
	global_load_dwordx4 v[68:71], v[6:7], off
	global_load_dwordx4 v[72:75], v[6:7], off offset:1024
	global_load_dwordx4 v[76:79], v[6:7], off offset:2048
	global_load_dwordx4 v[146:149], v[6:7], off offset:3072
	v_lshl_add_u64 v[4:5], v[4:5], 0, s[4:5]
	global_load_dwordx4 v[238:241], v[4:5], off
	global_load_dwordx4 v[242:245], v[4:5], off offset:1024
	global_load_dwordx4 v[246:249], v[4:5], off offset:2048
	global_load_dwordx4 v[250:253], v[4:5], off offset:3072
	v_lshl_add_u64 v[4:5], v[4:5], 0, s[4:5]
	global_load_dwordx4 v[128:131], v[4:5], off
	global_load_dwordx4 v[132:135], v[4:5], off offset:1024
	global_load_dwordx4 v[136:139], v[4:5], off offset:2048
	global_load_dwordx4 v[142:145], v[4:5], off offset:3072
	s_waitcnt vmcnt(20)
	s_waitcnt vmcnt(19)
	v_pk_add_f32 v[188:189], v[188:189], v[52:53]
	v_pk_add_f32 v[190:191], v[190:191], v[54:55]
	global_store_dwordx4 v[8:9], v[188:191], off
	s_waitcnt vmcnt(19)
	v_pk_add_f32 v[192:193], v[192:193], v[56:57]
	v_pk_add_f32 v[194:195], v[194:195], v[58:59]
	global_store_dwordx4 v[8:9], v[192:195], off offset:1024
	s_waitcnt vmcnt(19)
	v_pk_add_f32 v[196:197], v[196:197], v[60:61]
	v_pk_add_f32 v[198:199], v[198:199], v[62:63]
	global_store_dwordx4 v[8:9], v[196:199], off offset:2048
	s_waitcnt vmcnt(19)
	v_pk_add_f32 v[200:201], v[200:201], v[64:65]
	v_pk_add_f32 v[202:203], v[202:203], v[66:67]
	global_store_dwordx4 v[8:9], v[200:203], off offset:3072
	v_lshl_add_u64 v[6:7], v[6:7], 0, s[4:5]
	global_load_dwordx4 v[52:55], v[6:7], off
	global_load_dwordx4 v[56:59], v[6:7], off offset:1024
	global_load_dwordx4 v[60:63], v[6:7], off offset:2048
	global_load_dwordx4 v[64:67], v[6:7], off offset:3072
	v_lshl_add_u64 v[8:9], v[8:9], 0, s[4:5]
	s_waitcnt vmcnt(20)
	s_waitcnt vmcnt(19)
	v_pk_add_f32 v[204:205], v[204:205], v[68:69]
	v_pk_add_f32 v[206:207], v[206:207], v[70:71]
	global_store_dwordx4 v[8:9], v[204:207], off
	s_waitcnt vmcnt(19)
	v_pk_add_f32 v[208:209], v[208:209], v[72:73]
	v_pk_add_f32 v[210:211], v[210:211], v[74:75]
	global_store_dwordx4 v[8:9], v[208:211], off offset:1024
	s_waitcnt vmcnt(19)
	v_pk_add_f32 v[212:213], v[212:213], v[76:77]
	v_pk_add_f32 v[214:215], v[214:215], v[78:79]
	global_store_dwordx4 v[8:9], v[212:215], off offset:2048
	s_waitcnt vmcnt(19)
	v_pk_add_f32 v[234:235], v[234:235], v[146:147]
	v_pk_add_f32 v[236:237], v[236:237], v[148:149]
	global_store_dwordx4 v[8:9], v[234:237], off offset:3072
	v_lshl_add_u64 v[6:7], v[6:7], 0, s[4:5]
	global_load_dwordx4 v[68:71], v[6:7], off
	global_load_dwordx4 v[72:75], v[6:7], off offset:1024
	global_load_dwordx4 v[76:79], v[6:7], off offset:2048
	global_load_dwordx4 v[146:149], v[6:7], off offset:3072
	v_lshl_add_u64 v[8:9], v[8:9], 0, s[4:5]
	s_waitcnt vmcnt(20)
	s_waitcnt vmcnt(11)
	v_pk_add_f32 v[238:239], v[238:239], v[52:53]
	v_pk_add_f32 v[240:241], v[240:241], v[54:55]
	global_store_dwordx4 v[8:9], v[238:241], off
	s_waitcnt vmcnt(11)
	v_pk_add_f32 v[242:243], v[242:243], v[56:57]
	v_pk_add_f32 v[244:245], v[244:245], v[58:59]
	global_store_dwordx4 v[8:9], v[242:245], off offset:1024
	s_waitcnt vmcnt(11)
	v_pk_add_f32 v[246:247], v[246:247], v[60:61]
	v_pk_add_f32 v[248:249], v[248:249], v[62:63]
	global_store_dwordx4 v[8:9], v[246:249], off offset:2048
	s_waitcnt vmcnt(11)
	v_pk_add_f32 v[250:251], v[250:251], v[64:65]
	v_pk_add_f32 v[252:253], v[252:253], v[66:67]
	global_store_dwordx4 v[8:9], v[250:253], off offset:3072
	v_lshl_add_u64 v[8:9], v[8:9], 0, s[4:5]
	s_waitcnt vmcnt(20)
	s_waitcnt vmcnt(7)
	v_pk_add_f32 v[128:129], v[128:129], v[68:69]
	v_pk_add_f32 v[130:131], v[130:131], v[70:71]
	global_store_dwordx4 v[8:9], v[128:131], off
	s_waitcnt vmcnt(7)
	v_pk_add_f32 v[132:133], v[132:133], v[72:73]
	v_pk_add_f32 v[134:135], v[134:135], v[74:75]
	global_store_dwordx4 v[8:9], v[132:135], off offset:1024
	s_waitcnt vmcnt(7)
	v_pk_add_f32 v[136:137], v[136:137], v[76:77]
	v_pk_add_f32 v[138:139], v[138:139], v[78:79]
	global_store_dwordx4 v[8:9], v[136:139], off offset:2048
	s_waitcnt vmcnt(7)
	v_pk_add_f32 v[142:143], v[142:143], v[146:147]
	v_pk_add_f32 v[144:145], v[144:145], v[148:149]
	global_store_dwordx4 v[8:9], v[142:145], off offset:3072
	v_pk_mul_f32 v[18:19], v[188:189], v[188:189]
	v_pk_mul_f32 v[170:171], v[190:191], v[190:191]
	v_add_f32_e32 v44, v19, v18
	v_add_f32_e32 v44, v170, v44
	v_add_f32_e32 v44, v171, v44
	v_pk_mul_f32 v[18:19], v[192:193], v[192:193]
	v_pk_mul_f32 v[170:171], v[194:195], v[194:195]
	v_add_f32_e32 v45, v19, v18
	v_add_f32_e32 v45, v170, v45
	v_add_f32_e32 v45, v171, v45
	v_pk_mul_f32 v[18:19], v[196:197], v[196:197]
	v_pk_mul_f32 v[170:171], v[198:199], v[198:199]
	v_add_f32_e32 v46, v19, v18
	v_add_f32_e32 v46, v170, v46
	v_add_f32_e32 v46, v171, v46
	v_pk_mul_f32 v[18:19], v[200:201], v[200:201]
	v_pk_mul_f32 v[170:171], v[202:203], v[202:203]
	v_add_f32_e32 v47, v19, v18
	v_add_f32_e32 v47, v170, v47
	v_add_f32_e32 v47, v171, v47
	v_add_f32_e32 v158, v44, v45
	v_add_f32_e32 v158, v158, v46
	v_add_f32_e32 v158, v158, v47
	v_pk_mul_f32 v[18:19], v[204:205], v[204:205]
	v_pk_mul_f32 v[170:171], v[206:207], v[206:207]
	v_add_f32_e32 v44, v19, v18
	v_add_f32_e32 v44, v170, v44
	v_add_f32_e32 v44, v171, v44
	v_pk_mul_f32 v[18:19], v[208:209], v[208:209]
	v_pk_mul_f32 v[170:171], v[210:211], v[210:211]
	v_add_f32_e32 v45, v19, v18
	v_add_f32_e32 v45, v170, v45
	v_add_f32_e32 v45, v171, v45
	v_pk_mul_f32 v[18:19], v[212:213], v[212:213]
	v_pk_mul_f32 v[170:171], v[214:215], v[214:215]
	v_add_f32_e32 v46, v19, v18
	v_add_f32_e32 v46, v170, v46
	v_add_f32_e32 v46, v171, v46
	v_pk_mul_f32 v[18:19], v[234:235], v[234:235]
	v_pk_mul_f32 v[170:171], v[236:237], v[236:237]
	v_add_f32_e32 v47, v19, v18
	v_add_f32_e32 v47, v170, v47
	v_add_f32_e32 v47, v171, v47
	v_add_f32_e32 v160, v44, v45
	v_add_f32_e32 v160, v160, v46
	v_add_f32_e32 v160, v160, v47
	v_pk_mul_f32 v[18:19], v[238:239], v[238:239]
	v_pk_mul_f32 v[170:171], v[240:241], v[240:241]
	v_add_f32_e32 v44, v19, v18
	v_add_f32_e32 v44, v170, v44
	v_add_f32_e32 v44, v171, v44
	v_pk_mul_f32 v[18:19], v[242:243], v[242:243]
	v_pk_mul_f32 v[170:171], v[244:245], v[244:245]
	v_add_f32_e32 v45, v19, v18
	v_add_f32_e32 v45, v170, v45
	v_add_f32_e32 v45, v171, v45
	v_pk_mul_f32 v[18:19], v[246:247], v[246:247]
	v_pk_mul_f32 v[170:171], v[248:249], v[248:249]
	v_add_f32_e32 v46, v19, v18
	v_add_f32_e32 v46, v170, v46
	v_add_f32_e32 v46, v171, v46
	v_pk_mul_f32 v[18:19], v[250:251], v[250:251]
	v_pk_mul_f32 v[170:171], v[252:253], v[252:253]
	v_add_f32_e32 v47, v19, v18
	v_add_f32_e32 v47, v170, v47
	v_add_f32_e32 v47, v171, v47
	v_add_f32_e32 v162, v44, v45
	v_add_f32_e32 v162, v162, v46
	v_add_f32_e32 v162, v162, v47
	v_pk_mul_f32 v[18:19], v[128:129], v[128:129]
	v_pk_mul_f32 v[170:171], v[130:131], v[130:131]
	v_add_f32_e32 v44, v19, v18
	v_add_f32_e32 v44, v170, v44
	v_add_f32_e32 v44, v171, v44
	v_pk_mul_f32 v[18:19], v[132:133], v[132:133]
	v_pk_mul_f32 v[170:171], v[134:135], v[134:135]
	v_add_f32_e32 v45, v19, v18
	v_add_f32_e32 v45, v170, v45
	v_add_f32_e32 v45, v171, v45
	v_pk_mul_f32 v[18:19], v[136:137], v[136:137]
	v_pk_mul_f32 v[170:171], v[138:139], v[138:139]
	v_add_f32_e32 v46, v19, v18
	v_add_f32_e32 v46, v170, v46
	v_add_f32_e32 v46, v171, v46
	v_pk_mul_f32 v[18:19], v[142:143], v[142:143]
	v_pk_mul_f32 v[170:171], v[144:145], v[144:145]
	v_add_f32_e32 v47, v19, v18
	v_add_f32_e32 v47, v170, v47
	v_add_f32_e32 v47, v171, v47
	v_add_f32_e32 v164, v44, v45
	v_add_f32_e32 v164, v164, v46
	v_add_f32_e32 v164, v164, v47
	s_nop 1
	v_add_f32_dpp v158, v158, v158 quad_perm:[1,0,3,2] row_mask:0xf bank_mask:0xf
	v_add_f32_dpp v160, v160, v160 quad_perm:[1,0,3,2] row_mask:0xf bank_mask:0xf
	v_add_f32_dpp v162, v162, v162 quad_perm:[1,0,3,2] row_mask:0xf bank_mask:0xf
	v_add_f32_dpp v164, v164, v164 quad_perm:[1,0,3,2] row_mask:0xf bank_mask:0xf
	v_add_f32_dpp v158, v158, v158 quad_perm:[2,3,0,1] row_mask:0xf bank_mask:0xf
	v_add_f32_dpp v160, v160, v160 quad_perm:[2,3,0,1] row_mask:0xf bank_mask:0xf
	v_add_f32_dpp v162, v162, v162 quad_perm:[2,3,0,1] row_mask:0xf bank_mask:0xf
	v_add_f32_dpp v164, v164, v164 quad_perm:[2,3,0,1] row_mask:0xf bank_mask:0xf
	v_add_f32_dpp v158, v158, v158 row_half_mirror row_mask:0xf bank_mask:0xf
	v_add_f32_dpp v160, v160, v160 row_half_mirror row_mask:0xf bank_mask:0xf
	v_add_f32_dpp v162, v162, v162 row_half_mirror row_mask:0xf bank_mask:0xf
	v_add_f32_dpp v164, v164, v164 row_half_mirror row_mask:0xf bank_mask:0xf
	v_add_f32_dpp v158, v158, v158 row_mirror row_mask:0xf bank_mask:0xf
	v_add_f32_dpp v160, v160, v160 row_mirror row_mask:0xf bank_mask:0xf
	v_add_f32_dpp v162, v162, v162 row_mirror row_mask:0xf bank_mask:0xf
	v_add_f32_dpp v164, v164, v164 row_mirror row_mask:0xf bank_mask:0xf
	v_mov_b32_e32 v166, v158
	v_mov_b32_e32 v167, v160
	v_mov_b32_e32 v168, v162
	v_mov_b32_e32 v169, v164
	v_permlane16_swap_b32 v158, v166
	v_permlane16_swap_b32 v160, v167
	v_permlane16_swap_b32 v162, v168
	v_permlane16_swap_b32 v164, v169
	v_add_f32_e32 v158, v158, v166
	v_add_f32_e32 v160, v160, v167
	v_add_f32_e32 v162, v162, v168
	v_add_f32_e32 v164, v164, v169
	v_mov_b32_e32 v166, v158
	v_mov_b32_e32 v167, v160
	v_mov_b32_e32 v168, v162
	v_mov_b32_e32 v169, v164
	v_permlane32_swap_b32 v158, v166
	v_permlane32_swap_b32 v160, v167
	v_permlane32_swap_b32 v162, v168
	v_permlane32_swap_b32 v164, v169
	v_add_f32_e32 v158, v158, v166
	v_add_f32_e32 v160, v160, v167
	v_add_f32_e32 v162, v162, v168
	v_add_f32_e32 v164, v164, v169
	v_pk_add_f32 v[112:113], v[112:113], 1.0 op_sel_hi:[1,0]
	v_pk_add_f32 v[114:115], v[114:115], 1.0 op_sel_hi:[1,0]
	v_pk_add_f32 v[116:117], v[116:117], 1.0 op_sel_hi:[1,0]
	v_pk_add_f32 v[118:119], v[118:119], 1.0 op_sel_hi:[1,0]
	v_pk_add_f32 v[120:121], v[120:121], 1.0 op_sel_hi:[1,0]
	v_pk_add_f32 v[122:123], v[122:123], 1.0 op_sel_hi:[1,0]
	v_pk_add_f32 v[124:125], v[124:125], 1.0 op_sel_hi:[1,0]
	v_pk_add_f32 v[126:127], v[126:127], 1.0 op_sel_hi:[1,0]
	v_fmamk_f32 v158, v158, 0x3a800000, v218
	v_mul_f32_e32 v170, 0x4b800000, v158
	v_cmp_gt_f32_e32 vcc, s71, v158
	s_nop 1
	v_cndmask_b32_e32 v158, v158, v170, vcc
	v_rsq_f32_e32 v158, v158
	s_nop 0
	v_mul_f32_e32 v170, 0x45800000, v158
	v_cndmask_b32_e32 v158, v158, v170, vcc
	v_fmamk_f32 v160, v160, 0x3a800000, v218
	v_mul_f32_e32 v170, 0x4b800000, v160
	v_cmp_gt_f32_e32 vcc, s71, v160
	s_nop 1
	v_cndmask_b32_e32 v160, v160, v170, vcc
	v_rsq_f32_e32 v160, v160
	s_nop 0
	v_mul_f32_e32 v170, 0x45800000, v160
	v_cndmask_b32_e32 v160, v160, v170, vcc
	v_fmamk_f32 v162, v162, 0x3a800000, v218
	v_mul_f32_e32 v170, 0x4b800000, v162
	v_cmp_gt_f32_e32 vcc, s71, v162
	s_nop 1
	v_cndmask_b32_e32 v162, v162, v170, vcc
	v_rsq_f32_e32 v162, v162
	s_nop 0
	v_mul_f32_e32 v170, 0x45800000, v162
	v_cndmask_b32_e32 v162, v162, v170, vcc
	v_fmamk_f32 v164, v164, 0x3a800000, v218
	v_mul_f32_e32 v170, 0x4b800000, v164
	v_cmp_gt_f32_e32 vcc, s71, v164
	s_nop 1
	v_cndmask_b32_e32 v164, v164, v170, vcc
	v_rsq_f32_e32 v164, v164
	s_nop 0
	v_mul_f32_e32 v170, 0x45800000, v164
	v_cndmask_b32_e32 v164, v164, v170, vcc
	s_mov_b64 s[18:19], 0x800
	v_lshlrev_b64 v[16:17], 11, v[42:43]
	v_lshl_add_u64 v[16:17], v[30:31], 0, v[16:17]
	v_pk_mul_f32 v[188:189], v[188:189], v[158:159] op_sel_hi:[1,0]
	v_pk_mul_f32 v[188:189], v[80:81], v[188:189]
	v_pk_fma_f32 v[188:189], v[112:113], v[188:189], v[96:97]
	v_pk_mul_f32 v[190:191], v[190:191], v[158:159] op_sel_hi:[1,0]
	v_pk_mul_f32 v[190:191], v[82:83], v[190:191]
	v_pk_fma_f32 v[190:191], v[114:115], v[190:191], v[98:99]
	v_cvt_pk_bf16_f32 v188, v188, v189
	v_cvt_pk_bf16_f32 v189, v190, v191
	global_store_dwordx2 v[16:17], v[188:189], off
	v_pk_mul_f32 v[192:193], v[192:193], v[158:159] op_sel_hi:[1,0]
	v_pk_mul_f32 v[192:193], v[84:85], v[192:193]
	v_pk_fma_f32 v[192:193], v[116:117], v[192:193], v[100:101]
	v_pk_mul_f32 v[194:195], v[194:195], v[158:159] op_sel_hi:[1,0]
	v_pk_mul_f32 v[194:195], v[86:87], v[194:195]
	v_pk_fma_f32 v[194:195], v[118:119], v[194:195], v[102:103]
	v_cvt_pk_bf16_f32 v192, v192, v193
	v_cvt_pk_bf16_f32 v193, v194, v195
	global_store_dwordx2 v[16:17], v[192:193], off offset:512
	v_pk_mul_f32 v[196:197], v[196:197], v[158:159] op_sel_hi:[1,0]
	v_pk_mul_f32 v[196:197], v[88:89], v[196:197]
	v_pk_fma_f32 v[196:197], v[120:121], v[196:197], v[104:105]
	v_pk_mul_f32 v[198:199], v[198:199], v[158:159] op_sel_hi:[1,0]
	v_pk_mul_f32 v[198:199], v[90:91], v[198:199]
	v_pk_fma_f32 v[198:199], v[122:123], v[198:199], v[106:107]
	v_cvt_pk_bf16_f32 v196, v196, v197
	v_cvt_pk_bf16_f32 v197, v198, v199
	global_store_dwordx2 v[16:17], v[196:197], off offset:1024
	v_pk_mul_f32 v[200:201], v[200:201], v[158:159] op_sel_hi:[1,0]
	v_pk_mul_f32 v[200:201], v[92:93], v[200:201]
	v_pk_fma_f32 v[200:201], v[124:125], v[200:201], v[108:109]
	v_pk_mul_f32 v[202:203], v[202:203], v[158:159] op_sel_hi:[1,0]
	v_pk_mul_f32 v[202:203], v[94:95], v[202:203]
	v_pk_fma_f32 v[202:203], v[126:127], v[202:203], v[110:111]
	v_cvt_pk_bf16_f32 v200, v200, v201
	v_cvt_pk_bf16_f32 v201, v202, v203
	global_store_dwordx2 v[16:17], v[200:201], off offset:1536
	v_lshl_add_u64 v[16:17], v[16:17], 0, s[18:19]
	v_pk_mul_f32 v[204:205], v[204:205], v[160:161] op_sel_hi:[1,0]
	v_pk_mul_f32 v[204:205], v[80:81], v[204:205]
	v_pk_fma_f32 v[204:205], v[112:113], v[204:205], v[96:97]
	v_pk_mul_f32 v[206:207], v[206:207], v[160:161] op_sel_hi:[1,0]
	v_pk_mul_f32 v[206:207], v[82:83], v[206:207]
	v_pk_fma_f32 v[206:207], v[114:115], v[206:207], v[98:99]
	v_cvt_pk_bf16_f32 v204, v204, v205
	v_cvt_pk_bf16_f32 v205, v206, v207
	global_store_dwordx2 v[16:17], v[204:205], off
	v_pk_mul_f32 v[208:209], v[208:209], v[160:161] op_sel_hi:[1,0]
	v_pk_mul_f32 v[208:209], v[84:85], v[208:209]
	v_pk_fma_f32 v[208:209], v[116:117], v[208:209], v[100:101]
	v_pk_mul_f32 v[210:211], v[210:211], v[160:161] op_sel_hi:[1,0]
	v_pk_mul_f32 v[210:211], v[86:87], v[210:211]
	v_pk_fma_f32 v[210:211], v[118:119], v[210:211], v[102:103]
	v_cvt_pk_bf16_f32 v208, v208, v209
	v_cvt_pk_bf16_f32 v209, v210, v211
	global_store_dwordx2 v[16:17], v[208:209], off offset:512
	v_pk_mul_f32 v[212:213], v[212:213], v[160:161] op_sel_hi:[1,0]
	v_pk_mul_f32 v[212:213], v[88:89], v[212:213]
	v_pk_fma_f32 v[212:213], v[120:121], v[212:213], v[104:105]
	v_pk_mul_f32 v[214:215], v[214:215], v[160:161] op_sel_hi:[1,0]
	v_pk_mul_f32 v[214:215], v[90:91], v[214:215]
	v_pk_fma_f32 v[214:215], v[122:123], v[214:215], v[106:107]
	v_cvt_pk_bf16_f32 v212, v212, v213
	v_cvt_pk_bf16_f32 v213, v214, v215
	global_store_dwordx2 v[16:17], v[212:213], off offset:1024
	v_pk_mul_f32 v[234:235], v[234:235], v[160:161] op_sel_hi:[1,0]
	v_pk_mul_f32 v[234:235], v[92:93], v[234:235]
	v_pk_fma_f32 v[234:235], v[124:125], v[234:235], v[108:109]
	v_pk_mul_f32 v[236:237], v[236:237], v[160:161] op_sel_hi:[1,0]
	v_pk_mul_f32 v[236:237], v[94:95], v[236:237]
	v_pk_fma_f32 v[236:237], v[126:127], v[236:237], v[110:111]
	v_cvt_pk_bf16_f32 v234, v234, v235
	v_cvt_pk_bf16_f32 v235, v236, v237
	global_store_dwordx2 v[16:17], v[234:235], off offset:1536
	v_lshl_add_u64 v[16:17], v[16:17], 0, s[18:19]
	v_pk_mul_f32 v[238:239], v[238:239], v[162:163] op_sel_hi:[1,0]
	v_pk_mul_f32 v[238:239], v[80:81], v[238:239]
	v_pk_fma_f32 v[238:239], v[112:113], v[238:239], v[96:97]
	v_pk_mul_f32 v[240:241], v[240:241], v[162:163] op_sel_hi:[1,0]
	v_pk_mul_f32 v[240:241], v[82:83], v[240:241]
	v_pk_fma_f32 v[240:241], v[114:115], v[240:241], v[98:99]
	v_cvt_pk_bf16_f32 v238, v238, v239
	v_cvt_pk_bf16_f32 v239, v240, v241
	global_store_dwordx2 v[16:17], v[238:239], off
	v_pk_mul_f32 v[242:243], v[242:243], v[162:163] op_sel_hi:[1,0]
	v_pk_mul_f32 v[242:243], v[84:85], v[242:243]
	v_pk_fma_f32 v[242:243], v[116:117], v[242:243], v[100:101]
	v_pk_mul_f32 v[244:245], v[244:245], v[162:163] op_sel_hi:[1,0]
	v_pk_mul_f32 v[244:245], v[86:87], v[244:245]
	v_pk_fma_f32 v[244:245], v[118:119], v[244:245], v[102:103]
	v_cvt_pk_bf16_f32 v242, v242, v243
	v_cvt_pk_bf16_f32 v243, v244, v245
	global_store_dwordx2 v[16:17], v[242:243], off offset:512
	v_pk_mul_f32 v[246:247], v[246:247], v[162:163] op_sel_hi:[1,0]
	v_pk_mul_f32 v[246:247], v[88:89], v[246:247]
	v_pk_fma_f32 v[246:247], v[120:121], v[246:247], v[104:105]
	v_pk_mul_f32 v[248:249], v[248:249], v[162:163] op_sel_hi:[1,0]
	v_pk_mul_f32 v[248:249], v[90:91], v[248:249]
	v_pk_fma_f32 v[248:249], v[122:123], v[248:249], v[106:107]
	v_cvt_pk_bf16_f32 v246, v246, v247
	v_cvt_pk_bf16_f32 v247, v248, v249
	global_store_dwordx2 v[16:17], v[246:247], off offset:1024
	v_pk_mul_f32 v[250:251], v[250:251], v[162:163] op_sel_hi:[1,0]
	v_pk_mul_f32 v[250:251], v[92:93], v[250:251]
	v_pk_fma_f32 v[250:251], v[124:125], v[250:251], v[108:109]
	v_pk_mul_f32 v[252:253], v[252:253], v[162:163] op_sel_hi:[1,0]
	v_pk_mul_f32 v[252:253], v[94:95], v[252:253]
	v_pk_fma_f32 v[252:253], v[126:127], v[252:253], v[110:111]
	v_cvt_pk_bf16_f32 v250, v250, v251
	v_cvt_pk_bf16_f32 v251, v252, v253
	global_store_dwordx2 v[16:17], v[250:251], off offset:1536
	v_lshl_add_u64 v[16:17], v[16:17], 0, s[18:19]
	v_pk_mul_f32 v[128:129], v[128:129], v[164:165] op_sel_hi:[1,0]
	v_pk_mul_f32 v[128:129], v[80:81], v[128:129]
	v_pk_fma_f32 v[128:129], v[112:113], v[128:129], v[96:97]
	v_pk_mul_f32 v[130:131], v[130:131], v[164:165] op_sel_hi:[1,0]
	v_pk_mul_f32 v[130:131], v[82:83], v[130:131]
	v_pk_fma_f32 v[130:131], v[114:115], v[130:131], v[98:99]
	v_cvt_pk_bf16_f32 v128, v128, v129
	v_cvt_pk_bf16_f32 v129, v130, v131
	global_store_dwordx2 v[16:17], v[128:129], off
	v_pk_mul_f32 v[132:133], v[132:133], v[164:165] op_sel_hi:[1,0]
	v_pk_mul_f32 v[132:133], v[84:85], v[132:133]
	v_pk_fma_f32 v[132:133], v[116:117], v[132:133], v[100:101]
	v_pk_mul_f32 v[134:135], v[134:135], v[164:165] op_sel_hi:[1,0]
	v_pk_mul_f32 v[134:135], v[86:87], v[134:135]
	v_pk_fma_f32 v[134:135], v[118:119], v[134:135], v[102:103]
	v_cvt_pk_bf16_f32 v132, v132, v133
	v_cvt_pk_bf16_f32 v133, v134, v135
	global_store_dwordx2 v[16:17], v[132:133], off offset:512
	v_pk_mul_f32 v[136:137], v[136:137], v[164:165] op_sel_hi:[1,0]
	v_pk_mul_f32 v[136:137], v[88:89], v[136:137]
	v_pk_fma_f32 v[136:137], v[120:121], v[136:137], v[104:105]
	v_pk_mul_f32 v[138:139], v[138:139], v[164:165] op_sel_hi:[1,0]
	v_pk_mul_f32 v[138:139], v[90:91], v[138:139]
	v_pk_fma_f32 v[138:139], v[122:123], v[138:139], v[106:107]
	v_cvt_pk_bf16_f32 v136, v136, v137
	v_cvt_pk_bf16_f32 v137, v138, v139
	global_store_dwordx2 v[16:17], v[136:137], off offset:1024
	v_pk_mul_f32 v[142:143], v[142:143], v[164:165] op_sel_hi:[1,0]
	v_pk_mul_f32 v[142:143], v[92:93], v[142:143]
	v_pk_fma_f32 v[142:143], v[124:125], v[142:143], v[108:109]
	v_pk_mul_f32 v[144:145], v[144:145], v[164:165] op_sel_hi:[1,0]
	v_pk_mul_f32 v[144:145], v[94:95], v[144:145]
	v_pk_fma_f32 v[144:145], v[126:127], v[144:145], v[110:111]
	v_cvt_pk_bf16_f32 v142, v142, v143
	v_cvt_pk_bf16_f32 v143, v144, v145
	global_store_dwordx2 v[16:17], v[142:143], off offset:1536
	s_branch .LBB0_869
